# hyena: coalesced batched conv epilogues, conv1 output stored channel-major then LDS transposer half-phase instead of 2-byte scatter
# speedup vs baseline: 1.0365x; 1.0365x over previous
; #define LAS __attribute__((address_space(3)))
; __device__ __forceinline__ unsigned xb_add(unsigned* p, unsigned v) { return __hip_atomic_fetch_add(p, v, __ATOMIC_RELAXED, __HIP_MEMORY_SCOPE_AGENT); }
; __device__ __forceinline__ unsigned xb_xcc_id() { return (unsigned)__builtin_amdgcn_s_getreg((3 << 11) | 20) & 0xFu; }
; __global__ __launch_bounds__(512, 2) void mk_fwd(Args a) {
;     extern __shared__ __attribute__((aligned(16))) unsigned char lds_raw[];
;     LAS unsigned char* lds = (LAS unsigned char*)lds_raw;
;     unsigned* bar = (unsigned*)a.ws;
;     unsigned xcc = 0u;
;     if (a.coop) { xcc = xb_xcc_id(); if (threadIdx.x == 0) (void)xb_add(&bar[XB_XCNT(xcc)], 1u); }
;     (void)xcc;
;     for (int ph = a.ph_lo; ph < a.ph_hi; ++ph) {
_Z6mk_fwd4Args:
	s_load_dwordx8 s[72:79], s[0:1], 0xc0
	s_mov_b32 s60, s2
	v_writelane_b32 v255, 0, 63
	s_waitcnt lgkmcnt(0)
	s_cmp_lg_u32 s78, 0
	s_cselect_b64 s[2:3], -1, 0
	v_writelane_b32 v253, s2, 0
	s_cmp_eq_u32 s78, 0
	s_nop 0
	v_writelane_b32 v253, s3, 1
	s_cbranch_scc1 .LBB0_5
	v_and_b32_e32 v1, 0x3ff, v0
	s_getreg_b32 s6, hwreg(HW_REG_XCC_ID, 0, 4)
	v_cmp_eq_u32_e32 vcc, 0, v1
	s_and_saveexec_b64 s[2:3], vcc
	s_cbranch_execz .LBB0_4
	s_mov_b64 s[4:5], exec
	v_mbcnt_lo_u32_b32 v1, s4, 0
	v_mbcnt_hi_u32_b32 v1, s5, v1
	v_cmp_eq_u32_e32 vcc, 0, v1
	s_and_b64 s[8:9], exec, vcc
	s_mov_b64 exec, s[8:9]
	s_cbranch_execz .LBB0_4
	s_lshl_b32 s6, s6, 8
	s_and_b32 s6, s6, 0xf00
	s_bcnt1_i32_b64 s4, s[4:5]
	v_mov_b32_e32 v1, s6
	v_mov_b32_e32 v2, s4
	global_atomic_add v1, v2, s[74:75] offset:1024

; __device__ __forceinline__ void run_phase(const Args& a0, int ph, LAS unsigned char* lds) {
;     ...
;     } else if (sub == 1) {
;         for (int rep = 0; rep < NREP(1); ++rep) for (int ch = c; ch < 256; ch += G) hyena_unit(a, L, ch, lds);
;         if (G == 256) {
;             for (int k = 0; k < 3; ++k) attnC_unit(a, 96 * (c & 7) + 32 * k + (c >> 3), lds);
;             __syncthreads();
;             for (int k = 0; k < 3; ++k) { attnA_unit(a, 96 * (c & 7) + 32 * k + (c >> 3), lds); __syncthreads(); }
;         } else {
;             for (int u = c; u < 768; u += G) attnC_unit(a, u, lds);
;             __syncthreads();
;             for (int u = c; u < 768; u += G) { attnA_unit(a, u, lds); __syncthreads(); }
;         }
.LBB0_157:
	v_writelane_b32 v255, s59, 1
	v_writelane_b32 v255, s94, 2
	s_andn2_b64 vcc, exec, s[0:1]
	s_nop 0
	v_writelane_b32 v255, s95, 3
	v_writelane_b32 v255, s90, 4
	s_nop 1
	v_writelane_b32 v255, s91, 5
	v_writelane_b32 v255, s88, 6
	s_mov_b32 s90, s4
	s_nop 0
	v_writelane_b32 v255, s89, 7
	v_writelane_b32 v255, s84, 8
	s_nop 1
	v_writelane_b32 v255, s85, 9
	v_writelane_b32 v255, s82, 10
	s_nop 1
	v_writelane_b32 v255, s83, 11
	v_writelane_b32 v255, s87, 12
	v_writelane_b32 v255, s90, 13
	s_nop 1
	v_writelane_b32 v255, s91, 14
	v_writelane_b32 v255, s96, 15
	s_nop 1
	v_writelane_b32 v255, s97, 16
	v_writelane_b32 v255, s62, 17
	s_nop 1
	v_writelane_b32 v255, s63, 18
	v_writelane_b32 v255, s72, 19
	s_nop 1
	v_writelane_b32 v255, s73, 20
	v_writelane_b32 v255, s74, 21
	v_writelane_b32 v255, s75, 22
	v_writelane_b32 v255, s76, 23
	v_writelane_b32 v255, s77, 24
	v_writelane_b32 v255, s78, 25
	v_writelane_b32 v255, s79, 26
	s_cbranch_vccnz .LBB0_284
	v_readlane_b32 s64, v255, 63
	s_cmp_eq_u32 s64, 0
	s_cbranch_scc1 .Lmix_normal
	v_readlane_b32 s12, v254, 55
	v_readlane_b32 s13, v254, 56
	v_readlane_b32 s60, v254, 20
	s_lshl_b32 s33, s60, 9
	s_add_u32 s62, s12, 0x3f8a000
	s_addc_u32 s63, s13, 0
	s_add_u32 s62, s62, s33
	s_addc_u32 s63, s63, 0
	s_lshl_b32 s33, s60, 19
	s_add_u32 s64, s12, 0x21f8a300
	s_addc_u32 s65, s13, 0
	s_add_u32 s64, s64, s33
	s_addc_u32 s65, s65, 0
	v_and_b32_e32 v0, 31, v225
	v_bfe_u32 v1, v225, 5, 1
	v_lshrrev_b32_e32 v2, 6, v225
	v_lshlrev_b32_e32 v12, 12, v0
	v_lshlrev_b32_e32 v13, 4, v0
	v_lshl_add_u32 v14, v2, 5, v1
	v_readfirstlane_b32 s66, v2
	s_waitcnt vmcnt(0) lgkmcnt(0)
	s_barrier
	s_lshl_b32 s66, s66, 4
	s_mov_b32 s67, 0
.Ltr_dma:
	s_add_u32 s33, s66, s67
	v_lshl_add_u32 v3, s33, 1, v1
	v_lshrrev_b32_e32 v4, 3, v3
	v_and_b32_e32 v4, 31, v4
	v_xor_b32_e32 v4, v0, v4
	v_lshlrev_b32_e32 v4, 4, v4
	v_lshl_or_b32 v4, v3, 17, v4
	s_lshl_b32 s49, s33, 10
	s_mov_b32 m0, s49
	s_nop 0
	global_load_lds_dwordx4 v4, s[62:63]
	s_add_u32 s67, s67, 1
	s_cmp_lt_u32 s67, 16
	s_cbranch_scc1 .Ltr_dma
	s_waitcnt vmcnt(0)
	s_barrier
	s_mov_b32 s67, 0
.Ltr_st:
	v_lshl_add_u32 v5, s67, 1, v14
	v_lshlrev_b32_e32 v6, 1, v5
	v_xor_b32_e32 v6, v13, v6
	v_add_u32_e32 v6, v12, v6
	ds_read_u16 v16, v6
	ds_read_u16 v17, v6 offset:512
	ds_read_u16 v18, v6 offset:1024
	ds_read_u16 v19, v6 offset:1536
	ds_read_u16 v20, v6 offset:2048
	ds_read_u16 v21, v6 offset:2560
	ds_read_u16 v22, v6 offset:3072
	ds_read_u16 v23, v6 offset:3584
	v_lshl_or_b32 v7, v5, 11, v13
	s_waitcnt lgkmcnt(0)
	v_lshl_or_b32 v8, v17, 16, v16
	v_lshl_or_b32 v9, v19, 16, v18
	v_lshl_or_b32 v10, v21, 16, v20
	v_lshl_or_b32 v11, v23, 16, v22
	global_store_dwordx4 v7, v[8:11], s[64:65]
	s_add_u32 s67, s67, 1
	s_cmp_lt_u32 s67, 16
	s_cbranch_scc1 .Ltr_st
	s_branch .LBB0_284
.Lmix_normal:
	v_readlane_b32 s64, v255, 6
	v_readlane_b32 s12, v254, 55
	v_readlane_b32 s66, v255, 4
	v_readlane_b32 s68, v255, 2
	s_cmpk_gt_i32 s64, 0xff
	s_movk_i32 s33, 0x7ff
	s_mov_b32 s49, 0x8000
	s_movk_i32 s52, 0x1000
	v_readlane_b32 s53, v253, 20
	s_movk_i32 s54, 0x800
	s_movk_i32 s55, 0xdff
	v_readlane_b32 s56, v253, 21
	s_movk_i32 s57, 0x2040
	s_movk_i32 s58, 0x7dff
	s_mov_b64 s[60:61], 0x200000
	v_readlane_b32 s13, v254, 56
	v_readlane_b32 s62, v254, 63
	v_readlane_b32 s67, v255, 5
	v_readlane_b32 s69, v255, 3
	v_readlane_b32 s65, v255, 7
	v_readlane_b32 s63, v255, 0
	s_cbranch_scc1 .LBB0_213
	v_readlane_b32 s0, v254, 59
	s_mov_b32 s6, s0
	s_mov_b32 s4, s6
	v_readlane_b32 s1, v254, 60
	v_writelane_b32 v254, s4, 59
	s_ashr_i32 s7, s0, 31
	s_mul_i32 s2, s6, 0x300
	v_writelane_b32 v254, s5, 60
	s_mul_i32 s4, s6, 0x900
	s_ashr_i32 s5, s4, 31
	s_lshl_b32 s34, s0, 9
	s_lshl_b64 s[0:1], s[6:7], 23
	s_ashr_i32 s3, s2, 31
	s_lshl_b64 s[4:5], s[4:5], 2
	s_add_u32 s35, s18, s4
	s_addc_u32 s36, s19, s5
	s_lshl_b64 s[2:3], s[2:3], 2
	s_add_u32 s37, s16, s2
	s_addc_u32 s38, s17, s3
	s_add_u32 s4, s12, 0x2f8a000
	s_addc_u32 s5, s13, 0
	s_add_u32 s39, s4, s0
	s_addc_u32 s40, s5, s1
	s_add_u32 s41, s12, 0x9f8a000
	s_addc_u32 s42, s13, 0
	s_add_u32 s2, s12, s0
	s_addc_u32 s3, s13, s1
	s_add_u32 s43, s2, 0x2f8a800
	s_addc_u32 s44, s3, 0
	s_add_u32 s45, s12, 0x7f8a000
	s_addc_u32 s46, s13, 0
	s_add_u32 s47, s12, 0x21f8a300
	s_addc_u32 s48, s13, 0
	s_ashr_i32 s65, s64, 31
	s_lshl_b64 s[2:3], s[64:65], 2
	s_add_u32 s2, s0, s2
	s_addc_u32 s3, s1, s3
	s_add_u32 s4, s4, s2
	s_addc_u32 s5, s5, s3
	s_ashr_i32 s63, s62, 31
	s_lshl_b64 s[6:7], s[62:63], 2
	s_lshl_b64 s[0:1], s[64:65], 17
	s_add_u32 s0, s12, s0
	s_addc_u32 s1, s13, s1
	s_add_u32 s8, s0, 0x3f8a0c0
	s_addc_u32 s9, s1, 0
	s_lshl_b64 s[10:11], s[62:63], 17
	s_add_u32 s2, s12, s2
	s_addc_u32 s3, s13, s3
	s_add_u32 s12, s2, 0x2f8a800
	s_addc_u32 s13, s3, 0
	s_add_u32 s16, s0, 0x9f8a0c0
	s_addc_u32 s17, s1, 0
	s_mov_b32 s18, s64
	s_branch .LBB0_161

; #define LAS __attribute__((address_space(3)))
; __device__ __forceinline__ int tidx() { int t = threadIdx.x; asm volatile("" : "+v"(t)); return t; }
; template <int EPI>
; __device__ __forceinline__ void hy_conv(const Args& a, int L, int c, const bf16_t* U, LAS unsigned char* lds) {
;     const int tid = tidx(), wid = tid >> 6, lane = tid & 63, n = lane & 31, h = lane >> 5;
;     const bf16_t* UC = (const bf16_t*)(a.ws + OFF_UC);
;     bf16_t* Z = (bf16_t*)(a.ws + OFF_Z) + (size_t)c * MTOK;
;     bf16_t* MIX = (bf16_t*)(a.ws + WS_MIX);
;     const float dbias = a.in[18][L * 512 + EPI * 256 + c];
;     const bf16_t* urow = U + (size_t)n * SEQ + 8 * h;
;     LAS const unsigned char* fbase = lds + (n & 7) * HY_CP;
;     const int foff = 8 * h - (n & ~7);
; #pragma unroll 1
;     for (int blk = 0; blk < 2; ++blk) {
;         const int tb = 8 * wid + 4 * blk;
;         f32x16 acc[4];
; #pragma unroll
;         for (int tt = 0; tt < 4; ++tt)
; #pragma unroll
;             for (int i = 0; i < 16; ++i) acc[tt][i] = 0.f;
;         bf16x8 an[4];
; #pragma unroll
;         for (int k = 0; k < 4; ++k) an[k] = *(const bf16x8*)(urow + 16 * k);
; #pragma unroll 1
;         for (int s0 = 0; s0 < SEQ; s0 += 64) {
;             bf16x8 ac[4];
; #pragma unroll
;             for (int k = 0; k < 4; ++k) ac[k] = an[k];
.LBB0_185:
	s_or_b64 exec, exec, s[0:1]
	s_lshl_b64 s[2:3], s[18:19], 17
	s_add_u32 s22, s66, s2
	s_addc_u32 s23, s67, s3
	s_add_u32 s20, s41, s2
	s_addc_u32 s21, s42, s3
	s_add_i32 s0, s18, s34
	s_ashr_i32 s1, s0, 31
	s_lshl_b64 s[0:1], s[0:1], 2
	s_add_u32 s0, s14, s0
	v_mov_b32_e32 v2, v225
	s_addc_u32 s1, s15, s1
	s_waitcnt lgkmcnt(0)
	s_barrier
	global_load_dword v184, v155, s[0:1]
	s_add_u32 s24, s22, 0x2000000
	s_addc_u32 s25, s23, 0
	v_and_b32_e32 v140, 31, v225
	v_bfe_u32 v141, v225, 5, 1
	v_lshrrev_b32_e32 v142, 6, v225
	v_and_b32_e32 v143, 15, v140
	v_xor_b32_e32 v143, v141, v143
	v_lshlrev_b32_e32 v143, 4, v143
	v_lshl_or_b32 v210, v140, 9, v143
	v_and_b32_e32 v143, 7, v140
	v_mul_u32_u24_e32 v211, 0x2040, v143
	v_lshrrev_b32_e32 v143, 3, v140
	v_sub_u32_e32 v143, v141, v143
	v_lshlrev_b32_e32 v143, 4, v143
	v_lshlrev_b32_e32 v144, 9, v142
	v_sub_u32_e32 v212, v143, v144
	v_lshl_add_u32 v143, v142, 2, v141
	v_and_b32_e32 v144, 15, v143
	v_xor_b32_e32 v144, v140, v144
	v_lshlrev_b32_e32 v144, 4, v144
	v_lshl_or_b32 v208, v143, 12, v144
	v_add_u32_e32 v143, 2, v143
	v_and_b32_e32 v144, 15, v143
	v_xor_b32_e32 v144, v140, v144
	v_lshlrev_b32_e32 v144, 4, v144
	v_lshl_or_b32 v209, v143, 12, v144
	v_readfirstlane_b32 s31, v142
	v_mov_b32_e32 v214, v212
	s_lshl_b32 s31, s31, 11
	v_mov_b32_e32 v0, 0
	v_mov_b32_e32 v1, 0
	v_mov_b32_e32 v2, 0
	v_mov_b32_e32 v3, 0
	v_mov_b32_e32 v4, 0
	v_mov_b32_e32 v5, 0
	v_mov_b32_e32 v6, 0
	v_mov_b32_e32 v7, 0
	v_mov_b32_e32 v8, 0
	v_mov_b32_e32 v9, 0
	v_mov_b32_e32 v10, 0
	v_mov_b32_e32 v11, 0
	v_mov_b32_e32 v12, 0
	v_mov_b32_e32 v13, 0
	v_mov_b32_e32 v14, 0
	v_mov_b32_e32 v15, 0
	v_mov_b32_e32 v16, 0
	v_mov_b32_e32 v17, 0
	v_mov_b32_e32 v18, 0
	v_mov_b32_e32 v19, 0
	v_mov_b32_e32 v20, 0
	v_mov_b32_e32 v21, 0
	v_mov_b32_e32 v22, 0
	v_mov_b32_e32 v23, 0
	v_mov_b32_e32 v24, 0
	v_mov_b32_e32 v25, 0
	v_mov_b32_e32 v26, 0
	v_mov_b32_e32 v27, 0
	v_mov_b32_e32 v28, 0
	v_mov_b32_e32 v29, 0
	v_mov_b32_e32 v30, 0
	v_mov_b32_e32 v31, 0
	v_mov_b32_e32 v32, 0
	v_mov_b32_e32 v33, 0
	v_mov_b32_e32 v34, 0
	v_mov_b32_e32 v35, 0
	v_mov_b32_e32 v36, 0
	v_mov_b32_e32 v37, 0
	v_mov_b32_e32 v38, 0
	v_mov_b32_e32 v39, 0
	v_mov_b32_e32 v40, 0
	v_mov_b32_e32 v41, 0
	v_mov_b32_e32 v42, 0
	v_mov_b32_e32 v43, 0
	v_mov_b32_e32 v44, 0
	v_mov_b32_e32 v45, 0
	v_mov_b32_e32 v46, 0
	v_mov_b32_e32 v47, 0
	v_mov_b32_e32 v48, 0
	v_mov_b32_e32 v49, 0
	v_mov_b32_e32 v50, 0
	v_mov_b32_e32 v51, 0
	v_mov_b32_e32 v52, 0
	v_mov_b32_e32 v53, 0
	v_mov_b32_e32 v54, 0
	v_mov_b32_e32 v55, 0
	v_mov_b32_e32 v56, 0
	v_mov_b32_e32 v57, 0
	v_mov_b32_e32 v58, 0
	v_mov_b32_e32 v59, 0
	v_mov_b32_e32 v60, 0
	v_mov_b32_e32 v61, 0
	v_mov_b32_e32 v62, 0
	v_mov_b32_e32 v63, 0
	s_mov_b32 s30, 0x18000
	s_add_i32 m0, s30, s31
	s_nop 0
	global_load_lds_dwordx4 v208, s[22:23]
	s_nop 0
	s_add_i32 m0, m0, 0x400
	s_nop 0
	global_load_lds_dwordx4 v209, s[22:23]
	s_add_u32 s28, s22, 0x200
	s_addc_u32 s29, s23, 0
	s_mov_b32 s30, 0x1c000
	s_add_i32 m0, s30, s31
	s_nop 0
	global_load_lds_dwordx4 v208, s[28:29]
	s_nop 0
	s_add_i32 m0, m0, 0x400
	s_nop 0
	global_load_lds_dwordx4 v209, s[28:29]
	s_add_u32 s28, s22, 0x400
	s_addc_u32 s29, s23, 0
	s_mov_b32 s30, 0x20000
	s_add_i32 m0, s30, s31
	s_nop 0
	global_load_lds_dwordx4 v208, s[28:29]
	s_nop 0
	s_add_i32 m0, m0, 0x400
	s_nop 0
	global_load_lds_dwordx4 v209, s[28:29]
	s_mov_b32 s26, 0
	s_mov_b32 s27, 0x18000
	v_add_u32_e32 v213, s27, v210
	s_waitcnt vmcnt(4)
	s_barrier
.Lhc0_blk:
	ds_read_b128 v[64:67], v213
	v_and_b32_e32 v153, 0x1ff0, v214
	v_add_u32_e32 v153, v211, v153
	ds_read_b128 v[120:123], v153
	v_add_u32_e32 v153, 0xffffffc0, v214
	v_and_b32_e32 v153, 0x1ff0, v153
	v_add_u32_e32 v153, v211, v153
	ds_read_b128 v[112:115], v153
	v_add_u32_e32 v153, 0xffffff80, v214
	v_and_b32_e32 v153, 0x1ff0, v153
	v_add_u32_e32 v153, v211, v153
	ds_read_b128 v[104:107], v153
	v_add_u32_e32 v153, 0xffffff40, v214
	v_and_b32_e32 v153, 0x1ff0, v153
	v_add_u32_e32 v153, v211, v153
	ds_read_b128 v[96:99], v153
	v_xor_b32_e32 v152, 0x20, v213
	ds_read_b128 v[68:71], v152
	v_add_u32_e32 v153, 0x20, v214
	v_and_b32_e32 v153, 0x1ff0, v153
	v_add_u32_e32 v153, v211, v153
	ds_read_b128 v[124:127], v153
	v_add_u32_e32 v153, 0xffffffe0, v214
	v_and_b32_e32 v153, 0x1ff0, v153
	v_add_u32_e32 v153, v211, v153
	ds_read_b128 v[116:119], v153
	v_add_u32_e32 v153, 0xffffffa0, v214
	v_and_b32_e32 v153, 0x1ff0, v153
	v_add_u32_e32 v153, v211, v153
	ds_read_b128 v[108:111], v153
	v_add_u32_e32 v153, 0xffffff60, v214
	v_and_b32_e32 v153, 0x1ff0, v153
	v_add_u32_e32 v153, v211, v153
	ds_read_b128 v[100:103], v153
	v_xor_b32_e32 v152, 0x40, v213
	ds_read_b128 v[72:75], v152
	v_add_u32_e32 v153, 0x40, v214
	v_and_b32_e32 v153, 0x1ff0, v153
	v_add_u32_e32 v153, v211, v153
	ds_read_b128 v[128:131], v153
	v_xor_b32_e32 v152, 0x60, v213
	ds_read_b128 v[76:79], v152
	v_add_u32_e32 v153, 0x60, v214
	v_and_b32_e32 v153, 0x1ff0, v153
	v_add_u32_e32 v153, v211, v153
	ds_read_b128 v[132:135], v153
	v_add_u32_e32 v214, 0x80, v214
; #define LAS __attribute__((address_space(3)))
; template <int EPI>
; __device__ __forceinline__ void hy_conv(const Args& a, int L, int c, const bf16_t* U, LAS unsigned char* lds) {
;     ...
;         for (int s0 = 0; s0 < SEQ; s0 += 64) {
;             bf16x8 ac[4];
; #pragma unroll
;             for (int k = 0; k < 4; ++k) ac[k] = an[k];
;             if (s0 + 64 < SEQ) {
; #pragma unroll
;                 for (int k = 0; k < 4; ++k) an[k] = *(const bf16x8*)(urow + s0 + 64 + 16 * k);
;             }
;             bf16x8 bfr[10];
;             const int D0 = s0 - 32 * tb + foff;
; #pragma unroll
;             for (int d = 0; d < 10; ++d) { const int x = (D0 + 16 * (d - 6)) & 4095; bfr[d] = *(const LAS bf16x8*)(fbase + x * 2); }
; #pragma unroll
;             for (int k = 0; k < 4; ++k)
; #pragma unroll
;                 for (int tt = 0; tt < 4; ++tt) acc[tt] = __builtin_amdgcn_mfma_f32_32x32x16_bf16(ac[k], bfr[k - 2 * tt + 6], acc[tt], 0, 0, 0);
;         }
.Lhc0_chunk:
	s_waitcnt lgkmcnt(0)
	v_mfma_f32_32x32x16_bf16 v[48:63], v[64:67], v[120:123], v[48:63]
	v_xor_b32_e32 v152, 0x80, v213
	ds_read_b128 v[80:83], v152
	v_mfma_f32_32x32x16_bf16 v[32:47], v[64:67], v[112:115], v[32:47]
	v_and_b32_e32 v153, 0x1ff0, v214
	v_add_u32_e32 v153, v211, v153
	ds_read_b128 v[196:199], v153
	v_mfma_f32_32x32x16_bf16 v[16:31], v[64:67], v[104:107], v[16:31]
	v_add_u32_e32 v153, 0xffffffc0, v214
	v_and_b32_e32 v153, 0x1ff0, v153
	v_add_u32_e32 v153, v211, v153
	ds_read_b128 v[188:191], v153
	v_mfma_f32_32x32x16_bf16 v[0:15], v[64:67], v[96:99], v[0:15]
	v_add_u32_e32 v153, 0xffffff80, v214
	v_and_b32_e32 v153, 0x1ff0, v153
	v_add_u32_e32 v153, v211, v153
	ds_read_b128 v[144:147], v153
	v_mfma_f32_32x32x16_bf16 v[48:63], v[68:71], v[124:127], v[48:63]
	v_add_u32_e32 v153, 0xffffff40, v214
	v_and_b32_e32 v153, 0x1ff0, v153
	v_add_u32_e32 v153, v211, v153
	ds_read_b128 v[136:139], v153
	v_mfma_f32_32x32x16_bf16 v[32:47], v[68:71], v[116:119], v[32:47]
	v_xor_b32_e32 v152, 0xa0, v213
	ds_read_b128 v[84:87], v152
	v_mfma_f32_32x32x16_bf16 v[16:31], v[68:71], v[108:111], v[16:31]
	v_add_u32_e32 v153, 0x20, v214
	v_and_b32_e32 v153, 0x1ff0, v153
	v_add_u32_e32 v153, v211, v153
	ds_read_b128 v[200:203], v153
	v_mfma_f32_32x32x16_bf16 v[0:15], v[68:71], v[100:103], v[0:15]
	v_add_u32_e32 v153, 0xffffffe0, v214
	v_and_b32_e32 v153, 0x1ff0, v153
	v_add_u32_e32 v153, v211, v153
	ds_read_b128 v[192:195], v153
	v_mfma_f32_32x32x16_bf16 v[48:63], v[72:75], v[128:131], v[48:63]
	v_add_u32_e32 v153, 0xffffffa0, v214
	v_and_b32_e32 v153, 0x1ff0, v153
	v_add_u32_e32 v153, v211, v153
	ds_read_b128 v[148:151], v153
	v_mfma_f32_32x32x16_bf16 v[32:47], v[72:75], v[120:123], v[32:47]
	v_add_u32_e32 v153, 0xffffff60, v214
	v_and_b32_e32 v153, 0x1ff0, v153
	v_add_u32_e32 v153, v211, v153
	ds_read_b128 v[140:143], v153
	v_mfma_f32_32x32x16_bf16 v[16:31], v[72:75], v[112:115], v[16:31]
	v_xor_b32_e32 v152, 0xc0, v213
	ds_read_b128 v[88:91], v152
	v_mfma_f32_32x32x16_bf16 v[0:15], v[72:75], v[104:107], v[0:15]
	v_add_u32_e32 v153, 0x40, v214
	v_and_b32_e32 v153, 0x1ff0, v153
	v_add_u32_e32 v153, v211, v153
	ds_read_b128 v[204:207], v153
	v_mfma_f32_32x32x16_bf16 v[48:63], v[76:79], v[132:135], v[48:63]
	v_xor_b32_e32 v152, 0xe0, v213
	ds_read_b128 v[92:95], v152
	v_mfma_f32_32x32x16_bf16 v[32:47], v[76:79], v[124:127], v[32:47]
	v_add_u32_e32 v153, 0x60, v214
	v_and_b32_e32 v153, 0x1ff0, v153
	v_add_u32_e32 v153, v211, v153
	ds_read_b128 v[216:219], v153
	v_mfma_f32_32x32x16_bf16 v[16:31], v[76:79], v[116:119], v[16:31]
	v_add_u32_e32 v214, 0x80, v214
	v_mfma_f32_32x32x16_bf16 v[0:15], v[76:79], v[108:111], v[0:15]
	s_waitcnt lgkmcnt(0)
	v_mfma_f32_32x32x16_bf16 v[48:63], v[80:83], v[196:199], v[48:63]
	v_xor_b32_e32 v152, 0x100, v213
	ds_read_b128 v[64:67], v152
	v_mfma_f32_32x32x16_bf16 v[32:47], v[80:83], v[188:191], v[32:47]
	v_and_b32_e32 v153, 0x1ff0, v214
	v_add_u32_e32 v153, v211, v153
	ds_read_b128 v[120:123], v153
	v_mfma_f32_32x32x16_bf16 v[16:31], v[80:83], v[144:147], v[16:31]
	v_add_u32_e32 v153, 0xffffffc0, v214
	v_and_b32_e32 v153, 0x1ff0, v153
	v_add_u32_e32 v153, v211, v153
	ds_read_b128 v[112:115], v153
	v_mfma_f32_32x32x16_bf16 v[0:15], v[80:83], v[136:139], v[0:15]
	v_add_u32_e32 v153, 0xffffff80, v214
	v_and_b32_e32 v153, 0x1ff0, v153
	v_add_u32_e32 v153, v211, v153
	ds_read_b128 v[104:107], v153
	v_mfma_f32_32x32x16_bf16 v[48:63], v[84:87], v[200:203], v[48:63]
	v_add_u32_e32 v153, 0xffffff40, v214
	v_and_b32_e32 v153, 0x1ff0, v153
	v_add_u32_e32 v153, v211, v153
	ds_read_b128 v[96:99], v153
	v_mfma_f32_32x32x16_bf16 v[32:47], v[84:87], v[192:195], v[32:47]
	v_xor_b32_e32 v152, 0x120, v213
	ds_read_b128 v[68:71], v152
	v_mfma_f32_32x32x16_bf16 v[16:31], v[84:87], v[148:151], v[16:31]
	v_add_u32_e32 v153, 0x20, v214
	v_and_b32_e32 v153, 0x1ff0, v153
	v_add_u32_e32 v153, v211, v153
	ds_read_b128 v[124:127], v153
	v_mfma_f32_32x32x16_bf16 v[0:15], v[84:87], v[140:143], v[0:15]
	v_add_u32_e32 v153, 0xffffffe0, v214
	v_and_b32_e32 v153, 0x1ff0, v153
	v_add_u32_e32 v153, v211, v153
	ds_read_b128 v[116:119], v153
	v_mfma_f32_32x32x16_bf16 v[48:63], v[88:91], v[204:207], v[48:63]
	v_add_u32_e32 v153, 0xffffffa0, v214
	v_and_b32_e32 v153, 0x1ff0, v153
	v_add_u32_e32 v153, v211, v153
	ds_read_b128 v[108:111], v153
	v_mfma_f32_32x32x16_bf16 v[32:47], v[88:91], v[196:199], v[32:47]
	v_add_u32_e32 v153, 0xffffff60, v214
	v_and_b32_e32 v153, 0x1ff0, v153
	v_add_u32_e32 v153, v211, v153
	ds_read_b128 v[100:103], v153
	v_mfma_f32_32x32x16_bf16 v[16:31], v[88:91], v[188:191], v[16:31]
	v_xor_b32_e32 v152, 0x140, v213
	ds_read_b128 v[72:75], v152
	v_mfma_f32_32x32x16_bf16 v[0:15], v[88:91], v[144:147], v[0:15]
	v_add_u32_e32 v153, 0x40, v214
	v_and_b32_e32 v153, 0x1ff0, v153
	v_add_u32_e32 v153, v211, v153
	ds_read_b128 v[128:131], v153
	v_mfma_f32_32x32x16_bf16 v[48:63], v[92:95], v[216:219], v[48:63]
	v_xor_b32_e32 v152, 0x160, v213
	ds_read_b128 v[76:79], v152
	v_mfma_f32_32x32x16_bf16 v[32:47], v[92:95], v[200:203], v[32:47]
	v_add_u32_e32 v153, 0x60, v214
	v_and_b32_e32 v153, 0x1ff0, v153
	v_add_u32_e32 v153, v211, v153
	ds_read_b128 v[132:135], v153
	v_mfma_f32_32x32x16_bf16 v[16:31], v[92:95], v[192:195], v[16:31]
	v_add_u32_e32 v214, 0x80, v214
	v_mfma_f32_32x32x16_bf16 v[0:15], v[92:95], v[148:151], v[0:15]
	s_waitcnt lgkmcnt(0)
; #define LAS __attribute__((address_space(3)))
; template <int EPI>
; __device__ __forceinline__ void hy_conv(const Args& a, int L, int c, const bf16_t* U, LAS unsigned char* lds) {
;     ...
;         for (int s0 = 0; s0 < SEQ; s0 += 64) {
;             bf16x8 ac[4];
; #pragma unroll
;             for (int k = 0; k < 4; ++k) ac[k] = an[k];
;             if (s0 + 64 < SEQ) {
; #pragma unroll
;                 for (int k = 0; k < 4; ++k) an[k] = *(const bf16x8*)(urow + s0 + 64 + 16 * k);
;             }
;             bf16x8 bfr[10];
;             const int D0 = s0 - 32 * tb + foff;
; #pragma unroll
;             for (int d = 0; d < 10; ++d) { const int x = (D0 + 16 * (d - 6)) & 4095; bfr[d] = *(const LAS bf16x8*)(fbase + x * 2); }
; #pragma unroll
;             for (int k = 0; k < 4; ++k)
; #pragma unroll
;                 for (int tt = 0; tt < 4; ++tt) acc[tt] = __builtin_amdgcn_mfma_f32_32x32x16_bf16(ac[k], bfr[k - 2 * tt + 6], acc[tt], 0, 0, 0);
;         }
	v_mfma_f32_32x32x16_bf16 v[48:63], v[64:67], v[120:123], v[48:63]
	v_xor_b32_e32 v152, 0x180, v213
	ds_read_b128 v[80:83], v152
	v_mfma_f32_32x32x16_bf16 v[32:47], v[64:67], v[112:115], v[32:47]
	v_and_b32_e32 v153, 0x1ff0, v214
	v_add_u32_e32 v153, v211, v153
	ds_read_b128 v[196:199], v153
	v_mfma_f32_32x32x16_bf16 v[16:31], v[64:67], v[104:107], v[16:31]
	v_add_u32_e32 v153, 0xffffffc0, v214
	v_and_b32_e32 v153, 0x1ff0, v153
	v_add_u32_e32 v153, v211, v153
	ds_read_b128 v[188:191], v153
	v_mfma_f32_32x32x16_bf16 v[0:15], v[64:67], v[96:99], v[0:15]
	v_add_u32_e32 v153, 0xffffff80, v214
	v_and_b32_e32 v153, 0x1ff0, v153
	v_add_u32_e32 v153, v211, v153
	ds_read_b128 v[144:147], v153
	v_mfma_f32_32x32x16_bf16 v[48:63], v[68:71], v[124:127], v[48:63]
	v_add_u32_e32 v153, 0xffffff40, v214
	v_and_b32_e32 v153, 0x1ff0, v153
	v_add_u32_e32 v153, v211, v153
	ds_read_b128 v[136:139], v153
	v_mfma_f32_32x32x16_bf16 v[32:47], v[68:71], v[116:119], v[32:47]
	v_xor_b32_e32 v152, 0x1a0, v213
	ds_read_b128 v[84:87], v152
	v_mfma_f32_32x32x16_bf16 v[16:31], v[68:71], v[108:111], v[16:31]
	v_add_u32_e32 v153, 0x20, v214
	v_and_b32_e32 v153, 0x1ff0, v153
	v_add_u32_e32 v153, v211, v153
	ds_read_b128 v[200:203], v153
	v_mfma_f32_32x32x16_bf16 v[0:15], v[68:71], v[100:103], v[0:15]
	v_add_u32_e32 v153, 0xffffffe0, v214
	v_and_b32_e32 v153, 0x1ff0, v153
	v_add_u32_e32 v153, v211, v153
	ds_read_b128 v[192:195], v153
	v_mfma_f32_32x32x16_bf16 v[48:63], v[72:75], v[128:131], v[48:63]
	v_add_u32_e32 v153, 0xffffffa0, v214
	v_and_b32_e32 v153, 0x1ff0, v153
	v_add_u32_e32 v153, v211, v153
	ds_read_b128 v[148:151], v153
	v_mfma_f32_32x32x16_bf16 v[32:47], v[72:75], v[120:123], v[32:47]
	v_add_u32_e32 v153, 0xffffff60, v214
	v_and_b32_e32 v153, 0x1ff0, v153
	v_add_u32_e32 v153, v211, v153
	ds_read_b128 v[140:143], v153
	v_mfma_f32_32x32x16_bf16 v[16:31], v[72:75], v[112:115], v[16:31]
	v_xor_b32_e32 v152, 0x1c0, v213
	ds_read_b128 v[88:91], v152
	v_mfma_f32_32x32x16_bf16 v[0:15], v[72:75], v[104:107], v[0:15]
	v_add_u32_e32 v153, 0x40, v214
	v_and_b32_e32 v153, 0x1ff0, v153
	v_add_u32_e32 v153, v211, v153
	ds_read_b128 v[204:207], v153
	v_mfma_f32_32x32x16_bf16 v[48:63], v[76:79], v[132:135], v[48:63]
	v_xor_b32_e32 v152, 0x1e0, v213
	ds_read_b128 v[92:95], v152
	v_mfma_f32_32x32x16_bf16 v[32:47], v[76:79], v[124:127], v[32:47]
	v_add_u32_e32 v153, 0x60, v214
	v_and_b32_e32 v153, 0x1ff0, v153
	v_add_u32_e32 v153, v211, v153
	ds_read_b128 v[216:219], v153
	v_mfma_f32_32x32x16_bf16 v[16:31], v[76:79], v[116:119], v[16:31]
	v_add_u32_e32 v214, 0x80, v214
	v_mfma_f32_32x32x16_bf16 v[0:15], v[76:79], v[108:111], v[0:15]
	s_waitcnt lgkmcnt(0)
	s_cmp_eq_u32 s26, 15
	s_cbranch_scc1 .Lhc0_last
	s_cmp_eq_u32 s26, 14
	s_cbranch_scc1 .Lhc0_w0
	s_and_b32 s30, s26, 14
	s_cmp_eq_u32 s30, 8
	s_cbranch_scc1 .Lhc0_wdone
	s_waitcnt vmcnt(2)
	s_branch .Lhc0_wdone

; #define LAS __attribute__((address_space(3)))
; __device__ __forceinline__ unsigned pk2(float lo, float hi) { unsigned r; asm("v_cvt_pk_bf16_f32 %0, %1, %2" : "=v"(r) : "v"(lo), "v"(hi)); return r; }
; __device__ __forceinline__ float bf2f(bf16_t b) { return __uint_as_float(((unsigned)b) << 16); }
; template <int EPI>
; __device__ __forceinline__ void hy_conv(const Args& a, int L, int c, const bf16_t* U, LAS unsigned char* lds) {
;     ...
;         for (int s0 = 0; s0 < SEQ; s0 += 64) {
;             bf16x8 ac[4];
; #pragma unroll
;             for (int k = 0; k < 4; ++k) ac[k] = an[k];
;             if (s0 + 64 < SEQ) {
; #pragma unroll
;                 for (int k = 0; k < 4; ++k) an[k] = *(const bf16x8*)(urow + s0 + 64 + 16 * k);
;             }
;             bf16x8 bfr[10];
;             const int D0 = s0 - 32 * tb + foff;
; #pragma unroll
;             for (int d = 0; d < 10; ++d) { const int x = (D0 + 16 * (d - 6)) & 4095; bfr[d] = *(const LAS bf16x8*)(fbase + x * 2); }
; #pragma unroll
;             for (int k = 0; k < 4; ++k)
; #pragma unroll
;                 for (int tt = 0; tt < 4; ++tt) acc[tt] = __builtin_amdgcn_mfma_f32_32x32x16_bf16(ac[k], bfr[k - 2 * tt + 6], acc[tt], 0, 0, 0);
;         }
; #pragma unroll
;         for (int tt = 0; tt < 4; ++tt)
; #pragma unroll
;             for (int i = 0; i < 16; ++i) {
;                 const int bb = (i & 3) + 8 * (i >> 2) + 4 * h, t = 32 * (tb + tt) + n;
;                 const size_t tok = (size_t)bb * SEQ + t;
;                 if (EPI == 0) {
;                     const float v = bf2f(UC[(size_t)c * MTOK + tok]), x1 = bf2f(UC[((size_t)256 + c) * MTOK + tok]);
;                     const float z = x1 * (acc[tt][i] + dbias * v);
;                     Z[tok] = (bf16_t)(pk2(z, 0.f) & 0xffffu);
.Lhc0_wdone:
	s_barrier
	s_add_u32 s30, s26, 3
	s_cmp_ge_u32 s30, 16
	s_cbranch_scc1 .Lhc0_nodma
	s_and_b32 s28, s30, 7
	s_lshl_b32 s28, s28, 9
	s_add_u32 s28, s22, s28
	s_addc_u32 s29, s23, 0
	s_add_i32 m0, s27, s31
	s_nop 0
	global_load_lds_dwordx4 v208, s[28:29]
	s_nop 0
	s_add_i32 m0, m0, 0x400
	s_nop 0
	global_load_lds_dwordx4 v209, s[28:29]
.Lhc0_nodma:
	s_add_u32 s27, s27, 0x4000
	s_cmp_lt_u32 s27, 0x24000
	s_cbranch_scc1 .Lhc0_r2
	s_mov_b32 s27, 0x18000
.Lhc0_r2:
	v_add_u32_e32 v215, s27, v210
	s_and_b32 s30, s26, 7
	s_cmp_eq_u32 s30, 7
	s_cbranch_scc1 .Lhc0_last
	v_mfma_f32_32x32x16_bf16 v[48:63], v[80:83], v[196:199], v[48:63]
	ds_read_b128 v[64:67], v215
	v_mfma_f32_32x32x16_bf16 v[32:47], v[80:83], v[188:191], v[32:47]
	v_and_b32_e32 v153, 0x1ff0, v214
	v_add_u32_e32 v153, v211, v153
	ds_read_b128 v[120:123], v153
	v_mfma_f32_32x32x16_bf16 v[16:31], v[80:83], v[144:147], v[16:31]
	v_add_u32_e32 v153, 0xffffffc0, v214
	v_and_b32_e32 v153, 0x1ff0, v153
	v_add_u32_e32 v153, v211, v153
	ds_read_b128 v[112:115], v153
	v_mfma_f32_32x32x16_bf16 v[0:15], v[80:83], v[136:139], v[0:15]
	v_add_u32_e32 v153, 0xffffff80, v214
	v_and_b32_e32 v153, 0x1ff0, v153
	v_add_u32_e32 v153, v211, v153
	ds_read_b128 v[104:107], v153
	v_mfma_f32_32x32x16_bf16 v[48:63], v[84:87], v[200:203], v[48:63]
	v_add_u32_e32 v153, 0xffffff40, v214
	v_and_b32_e32 v153, 0x1ff0, v153
	v_add_u32_e32 v153, v211, v153
	ds_read_b128 v[96:99], v153
	v_mfma_f32_32x32x16_bf16 v[32:47], v[84:87], v[192:195], v[32:47]
	v_xor_b32_e32 v152, 0x20, v215
	ds_read_b128 v[68:71], v152
	v_mfma_f32_32x32x16_bf16 v[16:31], v[84:87], v[148:151], v[16:31]
	v_add_u32_e32 v153, 0x20, v214
	v_and_b32_e32 v153, 0x1ff0, v153
	v_add_u32_e32 v153, v211, v153
	ds_read_b128 v[124:127], v153
	v_mfma_f32_32x32x16_bf16 v[0:15], v[84:87], v[140:143], v[0:15]
	v_add_u32_e32 v153, 0xffffffe0, v214
	v_and_b32_e32 v153, 0x1ff0, v153
	v_add_u32_e32 v153, v211, v153
	ds_read_b128 v[116:119], v153
	v_mfma_f32_32x32x16_bf16 v[48:63], v[88:91], v[204:207], v[48:63]
	v_add_u32_e32 v153, 0xffffffa0, v214
	v_and_b32_e32 v153, 0x1ff0, v153
	v_add_u32_e32 v153, v211, v153
	ds_read_b128 v[108:111], v153
	v_mfma_f32_32x32x16_bf16 v[32:47], v[88:91], v[196:199], v[32:47]
	v_add_u32_e32 v153, 0xffffff60, v214
	v_and_b32_e32 v153, 0x1ff0, v153
	v_add_u32_e32 v153, v211, v153
	ds_read_b128 v[100:103], v153
	v_mfma_f32_32x32x16_bf16 v[16:31], v[88:91], v[188:191], v[16:31]
	v_xor_b32_e32 v152, 0x40, v215
	ds_read_b128 v[72:75], v152
	v_mfma_f32_32x32x16_bf16 v[0:15], v[88:91], v[144:147], v[0:15]
	v_add_u32_e32 v153, 0x40, v214
	v_and_b32_e32 v153, 0x1ff0, v153
	v_add_u32_e32 v153, v211, v153
	ds_read_b128 v[128:131], v153
	v_mfma_f32_32x32x16_bf16 v[48:63], v[92:95], v[216:219], v[48:63]
	v_xor_b32_e32 v152, 0x60, v215
	ds_read_b128 v[76:79], v152
	v_mfma_f32_32x32x16_bf16 v[32:47], v[92:95], v[200:203], v[32:47]
	v_add_u32_e32 v153, 0x60, v214
	v_and_b32_e32 v153, 0x1ff0, v153
	v_add_u32_e32 v153, v211, v153
	ds_read_b128 v[132:135], v153
	v_mfma_f32_32x32x16_bf16 v[16:31], v[92:95], v[192:195], v[16:31]
	v_add_u32_e32 v214, 0x80, v214
	v_mfma_f32_32x32x16_bf16 v[0:15], v[92:95], v[148:151], v[0:15]
	v_mov_b32_e32 v213, v215
	s_add_u32 s26, s26, 1
	s_branch .Lhc0_chunk
.Lhc0_last:
	v_mfma_f32_32x32x16_bf16 v[48:63], v[80:83], v[196:199], v[48:63]
	v_mfma_f32_32x32x16_bf16 v[32:47], v[80:83], v[188:191], v[32:47]
	v_mfma_f32_32x32x16_bf16 v[16:31], v[80:83], v[144:147], v[16:31]
	v_mfma_f32_32x32x16_bf16 v[0:15], v[80:83], v[136:139], v[0:15]
	v_mfma_f32_32x32x16_bf16 v[48:63], v[84:87], v[200:203], v[48:63]
	v_mfma_f32_32x32x16_bf16 v[32:47], v[84:87], v[192:195], v[32:47]
	v_mfma_f32_32x32x16_bf16 v[16:31], v[84:87], v[148:151], v[16:31]
	v_mfma_f32_32x32x16_bf16 v[0:15], v[84:87], v[140:143], v[0:15]
	v_mfma_f32_32x32x16_bf16 v[48:63], v[88:91], v[204:207], v[48:63]
	v_mfma_f32_32x32x16_bf16 v[32:47], v[88:91], v[196:199], v[32:47]
	v_mfma_f32_32x32x16_bf16 v[16:31], v[88:91], v[188:191], v[16:31]
	v_mfma_f32_32x32x16_bf16 v[0:15], v[88:91], v[144:147], v[0:15]
	v_mfma_f32_32x32x16_bf16 v[48:63], v[92:95], v[216:219], v[48:63]
	v_mfma_f32_32x32x16_bf16 v[32:47], v[92:95], v[200:203], v[32:47]
	v_mfma_f32_32x32x16_bf16 v[16:31], v[92:95], v[192:195], v[16:31]
	v_mfma_f32_32x32x16_bf16 v[0:15], v[92:95], v[148:151], v[0:15]
	v_mov_b32_e32 v213, v215
	s_add_u32 s26, s26, 1
	s_lshr_b32 s30, s26, 3
	s_sub_u32 s30, s30, 1
	s_lshl_b32 s30, s30, 2
	v_and_b32_e32 v140, 31, v225
	v_bfe_u32 v141, v225, 5, 1
	v_lshrrev_b32_e32 v142, 6, v225
	v_lshlrev_b32_e32 v143, 1, v140
	v_lshl_or_b32 v143, v141, 14, v143
	v_lshl_or_b32 v143, v142, 9, v143
	s_lshl_b32 s28, s30, 6
	v_or_b32_e32 v143, s28, v143
	v_add_u32_e32 v141, 0x0, v143
	global_load_ushort v64, v141, s[22:23] offset:0
	global_load_ushort v96, v141, s[24:25] offset:0
	v_add_u32_e32 v141, 0x1000, v143
	global_load_ushort v65, v141, s[22:23] offset:0
	global_load_ushort v97, v141, s[24:25] offset:0
	v_add_u32_e32 v141, 0x2000, v143
	global_load_ushort v66, v141, s[22:23] offset:0
	global_load_ushort v98, v141, s[24:25] offset:0
	v_add_u32_e32 v141, 0x3000, v143
	global_load_ushort v67, v141, s[22:23] offset:0
	global_load_ushort v99, v141, s[24:25] offset:0
	v_add_u32_e32 v141, 0x8000, v143
	global_load_ushort v68, v141, s[22:23] offset:0
	global_load_ushort v100, v141, s[24:25] offset:0
	v_add_u32_e32 v141, 0x9000, v143
	global_load_ushort v69, v141, s[22:23] offset:0
	global_load_ushort v101, v141, s[24:25] offset:0
	v_add_u32_e32 v141, 0xa000, v143
	global_load_ushort v70, v141, s[22:23] offset:0
	global_load_ushort v102, v141, s[24:25] offset:0
	v_add_u32_e32 v141, 0xb000, v143
; __device__ __forceinline__ unsigned pk2(float lo, float hi) { unsigned r; asm("v_cvt_pk_bf16_f32 %0, %1, %2" : "=v"(r) : "v"(lo), "v"(hi)); return r; }
; __device__ __forceinline__ float bf2f(bf16_t b) { return __uint_as_float(((unsigned)b) << 16); }
; template <int EPI>
; __device__ __forceinline__ void hy_conv(const Args& a, int L, int c, const bf16_t* U, LAS unsigned char* lds) {
;     ...
; #pragma unroll
;         for (int tt = 0; tt < 4; ++tt)
; #pragma unroll
;             for (int i = 0; i < 16; ++i) {
;                 const int bb = (i & 3) + 8 * (i >> 2) + 4 * h, t = 32 * (tb + tt) + n;
;                 const size_t tok = (size_t)bb * SEQ + t;
;                 if (EPI == 0) {
;                     const float v = bf2f(UC[(size_t)c * MTOK + tok]), x1 = bf2f(UC[((size_t)256 + c) * MTOK + tok]);
;                     const float z = x1 * (acc[tt][i] + dbias * v);
;                     Z[tok] = (bf16_t)(pk2(z, 0.f) & 0xffffu);
;                 } else {
;                     const float zz = bf2f(Z[tok]), x2 = bf2f(UC[((size_t)512 + c) * MTOK + tok]);
;                     const float o = x2 * (acc[tt][i] + dbias * zz);
;                     MIX[tok * DM + 384 + c] = (bf16_t)(pk2(o, 0.f) & 0xffffu);
;                 }
;             }
	global_load_ushort v71, v141, s[22:23] offset:0
	global_load_ushort v103, v141, s[24:25] offset:0
	v_add_u32_e32 v141, 0x10000, v143
	global_load_ushort v72, v141, s[22:23] offset:0
	global_load_ushort v104, v141, s[24:25] offset:0
	v_add_u32_e32 v141, 0x11000, v143
	global_load_ushort v73, v141, s[22:23] offset:0
	global_load_ushort v105, v141, s[24:25] offset:0
	v_add_u32_e32 v141, 0x12000, v143
	global_load_ushort v74, v141, s[22:23] offset:0
	global_load_ushort v106, v141, s[24:25] offset:0
	v_add_u32_e32 v141, 0x13000, v143
	global_load_ushort v75, v141, s[22:23] offset:0
	global_load_ushort v107, v141, s[24:25] offset:0
	v_add_u32_e32 v141, 0x18000, v143
	global_load_ushort v76, v141, s[22:23] offset:0
	global_load_ushort v108, v141, s[24:25] offset:0
	v_add_u32_e32 v141, 0x19000, v143
	global_load_ushort v77, v141, s[22:23] offset:0
	global_load_ushort v109, v141, s[24:25] offset:0
	v_add_u32_e32 v141, 0x1a000, v143
	global_load_ushort v78, v141, s[22:23] offset:0
	global_load_ushort v110, v141, s[24:25] offset:0
	v_add_u32_e32 v141, 0x1b000, v143
	global_load_ushort v79, v141, s[22:23] offset:0
	global_load_ushort v111, v141, s[24:25] offset:0
	v_add_u32_e32 v141, 0x0, v143
	global_load_ushort v80, v141, s[22:23] offset:64
	global_load_ushort v112, v141, s[24:25] offset:64
	v_add_u32_e32 v141, 0x1000, v143
	global_load_ushort v81, v141, s[22:23] offset:64
	global_load_ushort v113, v141, s[24:25] offset:64
	v_add_u32_e32 v141, 0x2000, v143
	global_load_ushort v82, v141, s[22:23] offset:64
	global_load_ushort v114, v141, s[24:25] offset:64
	v_add_u32_e32 v141, 0x3000, v143
	global_load_ushort v83, v141, s[22:23] offset:64
	global_load_ushort v115, v141, s[24:25] offset:64
	v_add_u32_e32 v141, 0x8000, v143
	global_load_ushort v84, v141, s[22:23] offset:64
	global_load_ushort v116, v141, s[24:25] offset:64
	v_add_u32_e32 v141, 0x9000, v143
	global_load_ushort v85, v141, s[22:23] offset:64
	global_load_ushort v117, v141, s[24:25] offset:64
	v_add_u32_e32 v141, 0xa000, v143
	global_load_ushort v86, v141, s[22:23] offset:64
	global_load_ushort v118, v141, s[24:25] offset:64
	v_add_u32_e32 v141, 0xb000, v143
	global_load_ushort v87, v141, s[22:23] offset:64
	global_load_ushort v119, v141, s[24:25] offset:64
	v_add_u32_e32 v141, 0x10000, v143
	global_load_ushort v88, v141, s[22:23] offset:64
	global_load_ushort v120, v141, s[24:25] offset:64
	v_add_u32_e32 v141, 0x11000, v143
	global_load_ushort v89, v141, s[22:23] offset:64
	global_load_ushort v121, v141, s[24:25] offset:64
	v_add_u32_e32 v141, 0x12000, v143
	global_load_ushort v90, v141, s[22:23] offset:64
	global_load_ushort v122, v141, s[24:25] offset:64
	v_add_u32_e32 v141, 0x13000, v143
	global_load_ushort v91, v141, s[22:23] offset:64
	global_load_ushort v123, v141, s[24:25] offset:64
	v_add_u32_e32 v141, 0x18000, v143
	global_load_ushort v92, v141, s[22:23] offset:64
	global_load_ushort v124, v141, s[24:25] offset:64
	v_add_u32_e32 v141, 0x19000, v143
	global_load_ushort v93, v141, s[22:23] offset:64
	global_load_ushort v125, v141, s[24:25] offset:64
	v_add_u32_e32 v141, 0x1a000, v143
	global_load_ushort v94, v141, s[22:23] offset:64
	global_load_ushort v126, v141, s[24:25] offset:64
	v_add_u32_e32 v141, 0x1b000, v143
	global_load_ushort v95, v141, s[22:23] offset:64
	global_load_ushort v127, v141, s[24:25] offset:64
	s_waitcnt vmcnt(62)
	v_lshlrev_b32_e32 v64, 16, v64
	v_lshlrev_b32_e32 v96, 16, v96
	v_fmac_f32_e32 v48, v184, v64
	v_mul_f32_e32 v48, v48, v96
	s_waitcnt vmcnt(60)
	v_lshlrev_b32_e32 v65, 16, v65
	v_lshlrev_b32_e32 v97, 16, v97
	v_fmac_f32_e32 v49, v184, v65
	v_mul_f32_e32 v49, v49, v97
	v_cvt_pk_bf16_f32 v64, v48, v49
	v_lshrrev_b32_e32 v65, 16, v64
	s_waitcnt vmcnt(58)
	v_lshlrev_b32_e32 v66, 16, v66
	v_lshlrev_b32_e32 v98, 16, v98
	v_fmac_f32_e32 v50, v184, v66
	v_mul_f32_e32 v50, v50, v98
	s_waitcnt vmcnt(56)
	v_lshlrev_b32_e32 v67, 16, v67
	v_lshlrev_b32_e32 v99, 16, v99
	v_fmac_f32_e32 v51, v184, v67
	v_mul_f32_e32 v51, v51, v99
	v_cvt_pk_bf16_f32 v66, v50, v51
	v_lshrrev_b32_e32 v67, 16, v66
	s_waitcnt vmcnt(54)
	v_lshlrev_b32_e32 v68, 16, v68
	v_lshlrev_b32_e32 v100, 16, v100
	v_fmac_f32_e32 v52, v184, v68
	v_mul_f32_e32 v52, v52, v100
	s_waitcnt vmcnt(52)
	v_lshlrev_b32_e32 v69, 16, v69
	v_lshlrev_b32_e32 v101, 16, v101
	v_fmac_f32_e32 v53, v184, v69
	v_mul_f32_e32 v53, v53, v101
	v_cvt_pk_bf16_f32 v68, v52, v53
	v_lshrrev_b32_e32 v69, 16, v68
	s_waitcnt vmcnt(50)
	v_lshlrev_b32_e32 v70, 16, v70
	v_lshlrev_b32_e32 v102, 16, v102
	v_fmac_f32_e32 v54, v184, v70
	v_mul_f32_e32 v54, v54, v102
	s_waitcnt vmcnt(48)
	v_lshlrev_b32_e32 v71, 16, v71
	v_lshlrev_b32_e32 v103, 16, v103
	v_fmac_f32_e32 v55, v184, v71
	v_mul_f32_e32 v55, v55, v103
	v_cvt_pk_bf16_f32 v70, v54, v55
	v_lshrrev_b32_e32 v71, 16, v70
	s_waitcnt vmcnt(46)
	v_lshlrev_b32_e32 v72, 16, v72
	v_lshlrev_b32_e32 v104, 16, v104
	v_fmac_f32_e32 v56, v184, v72
	v_mul_f32_e32 v56, v56, v104
	s_waitcnt vmcnt(44)
	v_lshlrev_b32_e32 v73, 16, v73
	v_lshlrev_b32_e32 v105, 16, v105
	v_fmac_f32_e32 v57, v184, v73
	v_mul_f32_e32 v57, v57, v105
	v_cvt_pk_bf16_f32 v72, v56, v57
	v_lshrrev_b32_e32 v73, 16, v72
	s_waitcnt vmcnt(42)
	v_lshlrev_b32_e32 v74, 16, v74
	v_lshlrev_b32_e32 v106, 16, v106
	v_fmac_f32_e32 v58, v184, v74
	v_mul_f32_e32 v58, v58, v106
	s_waitcnt vmcnt(40)
	v_lshlrev_b32_e32 v75, 16, v75
	v_lshlrev_b32_e32 v107, 16, v107
	v_fmac_f32_e32 v59, v184, v75
	v_mul_f32_e32 v59, v59, v107
	v_cvt_pk_bf16_f32 v74, v58, v59
	v_lshrrev_b32_e32 v75, 16, v74
	s_waitcnt vmcnt(38)
	v_lshlrev_b32_e32 v76, 16, v76
	v_lshlrev_b32_e32 v108, 16, v108
	v_fmac_f32_e32 v60, v184, v76
	v_mul_f32_e32 v60, v60, v108
	s_waitcnt vmcnt(36)
; __device__ __forceinline__ unsigned pk2(float lo, float hi) { unsigned r; asm("v_cvt_pk_bf16_f32 %0, %1, %2" : "=v"(r) : "v"(lo), "v"(hi)); return r; }
; __device__ __forceinline__ float bf2f(bf16_t b) { return __uint_as_float(((unsigned)b) << 16); }
; template <int EPI>
; __device__ __forceinline__ void hy_conv(const Args& a, int L, int c, const bf16_t* U, LAS unsigned char* lds) {
;     ...
; #pragma unroll
;         for (int tt = 0; tt < 4; ++tt)
; #pragma unroll
;             for (int i = 0; i < 16; ++i) {
;                 const int bb = (i & 3) + 8 * (i >> 2) + 4 * h, t = 32 * (tb + tt) + n;
;                 const size_t tok = (size_t)bb * SEQ + t;
;                 if (EPI == 0) {
;                     const float v = bf2f(UC[(size_t)c * MTOK + tok]), x1 = bf2f(UC[((size_t)256 + c) * MTOK + tok]);
;                     const float z = x1 * (acc[tt][i] + dbias * v);
;                     Z[tok] = (bf16_t)(pk2(z, 0.f) & 0xffffu);
;                 } else {
;                     const float zz = bf2f(Z[tok]), x2 = bf2f(UC[((size_t)512 + c) * MTOK + tok]);
;                     const float o = x2 * (acc[tt][i] + dbias * zz);
;                     MIX[tok * DM + 384 + c] = (bf16_t)(pk2(o, 0.f) & 0xffffu);
;                 }
;             }
	v_lshlrev_b32_e32 v77, 16, v77
	v_lshlrev_b32_e32 v109, 16, v109
	v_fmac_f32_e32 v61, v184, v77
	v_mul_f32_e32 v61, v61, v109
	v_cvt_pk_bf16_f32 v76, v60, v61
	v_lshrrev_b32_e32 v77, 16, v76
	s_waitcnt vmcnt(34)
	v_lshlrev_b32_e32 v78, 16, v78
	v_lshlrev_b32_e32 v110, 16, v110
	v_fmac_f32_e32 v62, v184, v78
	v_mul_f32_e32 v62, v62, v110
	s_waitcnt vmcnt(32)
	v_lshlrev_b32_e32 v79, 16, v79
	v_lshlrev_b32_e32 v111, 16, v111
	v_fmac_f32_e32 v63, v184, v79
	v_mul_f32_e32 v63, v63, v111
	v_cvt_pk_bf16_f32 v78, v62, v63
	v_lshrrev_b32_e32 v79, 16, v78
	s_waitcnt vmcnt(30)
	v_lshlrev_b32_e32 v80, 16, v80
	v_lshlrev_b32_e32 v112, 16, v112
	v_fmac_f32_e32 v32, v184, v80
	v_mul_f32_e32 v32, v32, v112
	s_waitcnt vmcnt(28)
	v_lshlrev_b32_e32 v81, 16, v81
	v_lshlrev_b32_e32 v113, 16, v113
	v_fmac_f32_e32 v33, v184, v81
	v_mul_f32_e32 v33, v33, v113
	v_cvt_pk_bf16_f32 v80, v32, v33
	v_lshrrev_b32_e32 v81, 16, v80
	s_waitcnt vmcnt(26)
	v_lshlrev_b32_e32 v82, 16, v82
	v_lshlrev_b32_e32 v114, 16, v114
	v_fmac_f32_e32 v34, v184, v82
	v_mul_f32_e32 v34, v34, v114
	s_waitcnt vmcnt(24)
	v_lshlrev_b32_e32 v83, 16, v83
	v_lshlrev_b32_e32 v115, 16, v115
	v_fmac_f32_e32 v35, v184, v83
	v_mul_f32_e32 v35, v35, v115
	v_cvt_pk_bf16_f32 v82, v34, v35
	v_lshrrev_b32_e32 v83, 16, v82
	s_waitcnt vmcnt(22)
	v_lshlrev_b32_e32 v84, 16, v84
	v_lshlrev_b32_e32 v116, 16, v116
	v_fmac_f32_e32 v36, v184, v84
	v_mul_f32_e32 v36, v36, v116
	s_waitcnt vmcnt(20)
	v_lshlrev_b32_e32 v85, 16, v85
	v_lshlrev_b32_e32 v117, 16, v117
	v_fmac_f32_e32 v37, v184, v85
	v_mul_f32_e32 v37, v37, v117
	v_cvt_pk_bf16_f32 v84, v36, v37
	v_lshrrev_b32_e32 v85, 16, v84
	s_waitcnt vmcnt(18)
	v_lshlrev_b32_e32 v86, 16, v86
	v_lshlrev_b32_e32 v118, 16, v118
	v_fmac_f32_e32 v38, v184, v86
	v_mul_f32_e32 v38, v38, v118
	s_waitcnt vmcnt(16)
	v_lshlrev_b32_e32 v87, 16, v87
	v_lshlrev_b32_e32 v119, 16, v119
	v_fmac_f32_e32 v39, v184, v87
	v_mul_f32_e32 v39, v39, v119
	v_cvt_pk_bf16_f32 v86, v38, v39
	v_lshrrev_b32_e32 v87, 16, v86
	s_waitcnt vmcnt(14)
	v_lshlrev_b32_e32 v88, 16, v88
	v_lshlrev_b32_e32 v120, 16, v120
	v_fmac_f32_e32 v40, v184, v88
	v_mul_f32_e32 v40, v40, v120
	s_waitcnt vmcnt(12)
	v_lshlrev_b32_e32 v89, 16, v89
	v_lshlrev_b32_e32 v121, 16, v121
	v_fmac_f32_e32 v41, v184, v89
	v_mul_f32_e32 v41, v41, v121
	v_cvt_pk_bf16_f32 v88, v40, v41
	v_lshrrev_b32_e32 v89, 16, v88
	s_waitcnt vmcnt(10)
	v_lshlrev_b32_e32 v90, 16, v90
	v_lshlrev_b32_e32 v122, 16, v122
	v_fmac_f32_e32 v42, v184, v90
	v_mul_f32_e32 v42, v42, v122
	s_waitcnt vmcnt(8)
	v_lshlrev_b32_e32 v91, 16, v91
	v_lshlrev_b32_e32 v123, 16, v123
	v_fmac_f32_e32 v43, v184, v91
	v_mul_f32_e32 v43, v43, v123
	v_cvt_pk_bf16_f32 v90, v42, v43
	v_lshrrev_b32_e32 v91, 16, v90
	s_waitcnt vmcnt(6)
	v_lshlrev_b32_e32 v92, 16, v92
	v_lshlrev_b32_e32 v124, 16, v124
	v_fmac_f32_e32 v44, v184, v92
	v_mul_f32_e32 v44, v44, v124
	s_waitcnt vmcnt(4)
	v_lshlrev_b32_e32 v93, 16, v93
	v_lshlrev_b32_e32 v125, 16, v125
	v_fmac_f32_e32 v45, v184, v93
	v_mul_f32_e32 v45, v45, v125
	v_cvt_pk_bf16_f32 v92, v44, v45
	v_lshrrev_b32_e32 v93, 16, v92
	s_waitcnt vmcnt(2)
	v_lshlrev_b32_e32 v94, 16, v94
	v_lshlrev_b32_e32 v126, 16, v126
	v_fmac_f32_e32 v46, v184, v94
	v_mul_f32_e32 v46, v46, v126
	s_waitcnt vmcnt(0)
	v_lshlrev_b32_e32 v95, 16, v95
	v_lshlrev_b32_e32 v127, 16, v127
	v_fmac_f32_e32 v47, v184, v95
	v_mul_f32_e32 v47, v47, v127
	v_cvt_pk_bf16_f32 v94, v46, v47
	v_lshrrev_b32_e32 v95, 16, v94
	v_add_u32_e32 v141, 0x0, v143
	global_store_short v141, v64, s[20:21] offset:0
	v_add_u32_e32 v141, 0x1000, v143
	global_store_short v141, v65, s[20:21] offset:0
	v_add_u32_e32 v141, 0x2000, v143
	global_store_short v141, v66, s[20:21] offset:0
	v_add_u32_e32 v141, 0x3000, v143
	global_store_short v141, v67, s[20:21] offset:0
	v_add_u32_e32 v141, 0x8000, v143
	global_store_short v141, v68, s[20:21] offset:0
	v_add_u32_e32 v141, 0x9000, v143
	global_store_short v141, v69, s[20:21] offset:0
	v_add_u32_e32 v141, 0xa000, v143
	global_store_short v141, v70, s[20:21] offset:0
	v_add_u32_e32 v141, 0xb000, v143
	global_store_short v141, v71, s[20:21] offset:0
	v_add_u32_e32 v141, 0x10000, v143
	global_store_short v141, v72, s[20:21] offset:0
	v_add_u32_e32 v141, 0x11000, v143
	global_store_short v141, v73, s[20:21] offset:0
	v_add_u32_e32 v141, 0x12000, v143
	global_store_short v141, v74, s[20:21] offset:0
	v_add_u32_e32 v141, 0x13000, v143
	global_store_short v141, v75, s[20:21] offset:0
	v_add_u32_e32 v141, 0x18000, v143
	global_store_short v141, v76, s[20:21] offset:0
	v_add_u32_e32 v141, 0x19000, v143
	global_store_short v141, v77, s[20:21] offset:0
	v_add_u32_e32 v141, 0x1a000, v143
	global_store_short v141, v78, s[20:21] offset:0
	v_add_u32_e32 v141, 0x1b000, v143
	global_store_short v141, v79, s[20:21] offset:0
	v_add_u32_e32 v141, 0x0, v143
	global_store_short v141, v80, s[20:21] offset:64
	v_add_u32_e32 v141, 0x1000, v143
	global_store_short v141, v81, s[20:21] offset:64
	v_add_u32_e32 v141, 0x2000, v143
	global_store_short v141, v82, s[20:21] offset:64
	v_add_u32_e32 v141, 0x3000, v143
	global_store_short v141, v83, s[20:21] offset:64
	v_add_u32_e32 v141, 0x8000, v143
	global_store_short v141, v84, s[20:21] offset:64
	v_add_u32_e32 v141, 0x9000, v143
	global_store_short v141, v85, s[20:21] offset:64
	v_add_u32_e32 v141, 0xa000, v143
	global_store_short v141, v86, s[20:21] offset:64
	v_add_u32_e32 v141, 0xb000, v143
	global_store_short v141, v87, s[20:21] offset:64
	v_add_u32_e32 v141, 0x10000, v143
	global_store_short v141, v88, s[20:21] offset:64
	v_add_u32_e32 v141, 0x11000, v143
	global_store_short v141, v89, s[20:21] offset:64
	v_add_u32_e32 v141, 0x12000, v143
; __device__ __forceinline__ unsigned pk2(float lo, float hi) { unsigned r; asm("v_cvt_pk_bf16_f32 %0, %1, %2" : "=v"(r) : "v"(lo), "v"(hi)); return r; }
; __device__ __forceinline__ float bf2f(bf16_t b) { return __uint_as_float(((unsigned)b) << 16); }
; template <int EPI>
; __device__ __forceinline__ void hy_conv(const Args& a, int L, int c, const bf16_t* U, LAS unsigned char* lds) {
;     ...
; #pragma unroll
;         for (int tt = 0; tt < 4; ++tt)
; #pragma unroll
;             for (int i = 0; i < 16; ++i) {
;                 const int bb = (i & 3) + 8 * (i >> 2) + 4 * h, t = 32 * (tb + tt) + n;
;                 const size_t tok = (size_t)bb * SEQ + t;
;                 if (EPI == 0) {
;                     const float v = bf2f(UC[(size_t)c * MTOK + tok]), x1 = bf2f(UC[((size_t)256 + c) * MTOK + tok]);
;                     const float z = x1 * (acc[tt][i] + dbias * v);
;                     Z[tok] = (bf16_t)(pk2(z, 0.f) & 0xffffu);
;                 } else {
;                     const float zz = bf2f(Z[tok]), x2 = bf2f(UC[((size_t)512 + c) * MTOK + tok]);
;                     const float o = x2 * (acc[tt][i] + dbias * zz);
;                     MIX[tok * DM + 384 + c] = (bf16_t)(pk2(o, 0.f) & 0xffffu);
;                 }
;             }
	global_store_short v141, v90, s[20:21] offset:64
	v_add_u32_e32 v141, 0x13000, v143
	global_store_short v141, v91, s[20:21] offset:64
	v_add_u32_e32 v141, 0x18000, v143
	global_store_short v141, v92, s[20:21] offset:64
	v_add_u32_e32 v141, 0x19000, v143
	global_store_short v141, v93, s[20:21] offset:64
	v_add_u32_e32 v141, 0x1a000, v143
	global_store_short v141, v94, s[20:21] offset:64
	v_add_u32_e32 v141, 0x1b000, v143
	global_store_short v141, v95, s[20:21] offset:64
	v_add_u32_e32 v141, 0x0, v143
	global_load_ushort v64, v141, s[22:23] offset:128
	global_load_ushort v96, v141, s[24:25] offset:128
	v_add_u32_e32 v141, 0x1000, v143
	global_load_ushort v65, v141, s[22:23] offset:128
	global_load_ushort v97, v141, s[24:25] offset:128
	v_add_u32_e32 v141, 0x2000, v143
	global_load_ushort v66, v141, s[22:23] offset:128
	global_load_ushort v98, v141, s[24:25] offset:128
	v_add_u32_e32 v141, 0x3000, v143
	global_load_ushort v67, v141, s[22:23] offset:128
	global_load_ushort v99, v141, s[24:25] offset:128
	v_add_u32_e32 v141, 0x8000, v143
	global_load_ushort v68, v141, s[22:23] offset:128
	global_load_ushort v100, v141, s[24:25] offset:128
	v_add_u32_e32 v141, 0x9000, v143
	global_load_ushort v69, v141, s[22:23] offset:128
	global_load_ushort v101, v141, s[24:25] offset:128
	v_add_u32_e32 v141, 0xa000, v143
	global_load_ushort v70, v141, s[22:23] offset:128
	global_load_ushort v102, v141, s[24:25] offset:128
	v_add_u32_e32 v141, 0xb000, v143
	global_load_ushort v71, v141, s[22:23] offset:128
	global_load_ushort v103, v141, s[24:25] offset:128
	v_add_u32_e32 v141, 0x10000, v143
	global_load_ushort v72, v141, s[22:23] offset:128
	global_load_ushort v104, v141, s[24:25] offset:128
	v_add_u32_e32 v141, 0x11000, v143
	global_load_ushort v73, v141, s[22:23] offset:128
	global_load_ushort v105, v141, s[24:25] offset:128
	v_add_u32_e32 v141, 0x12000, v143
	global_load_ushort v74, v141, s[22:23] offset:128
	global_load_ushort v106, v141, s[24:25] offset:128
	v_add_u32_e32 v141, 0x13000, v143
	global_load_ushort v75, v141, s[22:23] offset:128
	global_load_ushort v107, v141, s[24:25] offset:128
	v_add_u32_e32 v141, 0x18000, v143
	global_load_ushort v76, v141, s[22:23] offset:128
	global_load_ushort v108, v141, s[24:25] offset:128
	v_add_u32_e32 v141, 0x19000, v143
	global_load_ushort v77, v141, s[22:23] offset:128
	global_load_ushort v109, v141, s[24:25] offset:128
	v_add_u32_e32 v141, 0x1a000, v143
	global_load_ushort v78, v141, s[22:23] offset:128
	global_load_ushort v110, v141, s[24:25] offset:128
	v_add_u32_e32 v141, 0x1b000, v143
	global_load_ushort v79, v141, s[22:23] offset:128
	global_load_ushort v111, v141, s[24:25] offset:128
	v_add_u32_e32 v141, 0x0, v143
	global_load_ushort v80, v141, s[22:23] offset:192
	global_load_ushort v112, v141, s[24:25] offset:192
	v_add_u32_e32 v141, 0x1000, v143
	global_load_ushort v81, v141, s[22:23] offset:192
	global_load_ushort v113, v141, s[24:25] offset:192
	v_add_u32_e32 v141, 0x2000, v143
	global_load_ushort v82, v141, s[22:23] offset:192
	global_load_ushort v114, v141, s[24:25] offset:192
	v_add_u32_e32 v141, 0x3000, v143
	global_load_ushort v83, v141, s[22:23] offset:192
	global_load_ushort v115, v141, s[24:25] offset:192
	v_add_u32_e32 v141, 0x8000, v143
	global_load_ushort v84, v141, s[22:23] offset:192
	global_load_ushort v116, v141, s[24:25] offset:192
	v_add_u32_e32 v141, 0x9000, v143
	global_load_ushort v85, v141, s[22:23] offset:192
	global_load_ushort v117, v141, s[24:25] offset:192
	v_add_u32_e32 v141, 0xa000, v143
	global_load_ushort v86, v141, s[22:23] offset:192
	global_load_ushort v118, v141, s[24:25] offset:192
	v_add_u32_e32 v141, 0xb000, v143
	global_load_ushort v87, v141, s[22:23] offset:192
	global_load_ushort v119, v141, s[24:25] offset:192
	v_add_u32_e32 v141, 0x10000, v143
	global_load_ushort v88, v141, s[22:23] offset:192
	global_load_ushort v120, v141, s[24:25] offset:192
	v_add_u32_e32 v141, 0x11000, v143
	global_load_ushort v89, v141, s[22:23] offset:192
	global_load_ushort v121, v141, s[24:25] offset:192
	v_add_u32_e32 v141, 0x12000, v143
	global_load_ushort v90, v141, s[22:23] offset:192
	global_load_ushort v122, v141, s[24:25] offset:192
	v_add_u32_e32 v141, 0x13000, v143
	global_load_ushort v91, v141, s[22:23] offset:192
	global_load_ushort v123, v141, s[24:25] offset:192
	v_add_u32_e32 v141, 0x18000, v143
	global_load_ushort v92, v141, s[22:23] offset:192
	global_load_ushort v124, v141, s[24:25] offset:192
	v_add_u32_e32 v141, 0x19000, v143
	global_load_ushort v93, v141, s[22:23] offset:192
	global_load_ushort v125, v141, s[24:25] offset:192
	v_add_u32_e32 v141, 0x1a000, v143
	global_load_ushort v94, v141, s[22:23] offset:192
	global_load_ushort v126, v141, s[24:25] offset:192
	v_add_u32_e32 v141, 0x1b000, v143
	global_load_ushort v95, v141, s[22:23] offset:192
	global_load_ushort v127, v141, s[24:25] offset:192
	s_waitcnt vmcnt(62)
	v_lshlrev_b32_e32 v64, 16, v64
	v_lshlrev_b32_e32 v96, 16, v96
	v_fmac_f32_e32 v16, v184, v64
	v_mul_f32_e32 v16, v16, v96
	s_waitcnt vmcnt(60)
	v_lshlrev_b32_e32 v65, 16, v65
	v_lshlrev_b32_e32 v97, 16, v97
	v_fmac_f32_e32 v17, v184, v65
	v_mul_f32_e32 v17, v17, v97
	v_cvt_pk_bf16_f32 v64, v16, v17
	v_lshrrev_b32_e32 v65, 16, v64
	s_waitcnt vmcnt(58)
	v_lshlrev_b32_e32 v66, 16, v66
	v_lshlrev_b32_e32 v98, 16, v98
	v_fmac_f32_e32 v18, v184, v66
	v_mul_f32_e32 v18, v18, v98
	s_waitcnt vmcnt(56)
	v_lshlrev_b32_e32 v67, 16, v67
	v_lshlrev_b32_e32 v99, 16, v99
	v_fmac_f32_e32 v19, v184, v67
	v_mul_f32_e32 v19, v19, v99
	v_cvt_pk_bf16_f32 v66, v18, v19
	v_lshrrev_b32_e32 v67, 16, v66
	s_waitcnt vmcnt(54)
; __device__ __forceinline__ unsigned pk2(float lo, float hi) { unsigned r; asm("v_cvt_pk_bf16_f32 %0, %1, %2" : "=v"(r) : "v"(lo), "v"(hi)); return r; }
; __device__ __forceinline__ float bf2f(bf16_t b) { return __uint_as_float(((unsigned)b) << 16); }
; template <int EPI>
; __device__ __forceinline__ void hy_conv(const Args& a, int L, int c, const bf16_t* U, LAS unsigned char* lds) {
;     ...
; #pragma unroll
;         for (int tt = 0; tt < 4; ++tt)
; #pragma unroll
;             for (int i = 0; i < 16; ++i) {
;                 const int bb = (i & 3) + 8 * (i >> 2) + 4 * h, t = 32 * (tb + tt) + n;
;                 const size_t tok = (size_t)bb * SEQ + t;
;                 if (EPI == 0) {
;                     const float v = bf2f(UC[(size_t)c * MTOK + tok]), x1 = bf2f(UC[((size_t)256 + c) * MTOK + tok]);
;                     const float z = x1 * (acc[tt][i] + dbias * v);
;                     Z[tok] = (bf16_t)(pk2(z, 0.f) & 0xffffu);
;                 } else {
;                     const float zz = bf2f(Z[tok]), x2 = bf2f(UC[((size_t)512 + c) * MTOK + tok]);
;                     const float o = x2 * (acc[tt][i] + dbias * zz);
;                     MIX[tok * DM + 384 + c] = (bf16_t)(pk2(o, 0.f) & 0xffffu);
;                 }
;             }
	v_lshlrev_b32_e32 v68, 16, v68
	v_lshlrev_b32_e32 v100, 16, v100
	v_fmac_f32_e32 v20, v184, v68
	v_mul_f32_e32 v20, v20, v100
	s_waitcnt vmcnt(52)
	v_lshlrev_b32_e32 v69, 16, v69
	v_lshlrev_b32_e32 v101, 16, v101
	v_fmac_f32_e32 v21, v184, v69
	v_mul_f32_e32 v21, v21, v101
	v_cvt_pk_bf16_f32 v68, v20, v21
	v_lshrrev_b32_e32 v69, 16, v68
	s_waitcnt vmcnt(50)
	v_lshlrev_b32_e32 v70, 16, v70
	v_lshlrev_b32_e32 v102, 16, v102
	v_fmac_f32_e32 v22, v184, v70
	v_mul_f32_e32 v22, v22, v102
	s_waitcnt vmcnt(48)
	v_lshlrev_b32_e32 v71, 16, v71
	v_lshlrev_b32_e32 v103, 16, v103
	v_fmac_f32_e32 v23, v184, v71
	v_mul_f32_e32 v23, v23, v103
	v_cvt_pk_bf16_f32 v70, v22, v23
	v_lshrrev_b32_e32 v71, 16, v70
	s_waitcnt vmcnt(46)
	v_lshlrev_b32_e32 v72, 16, v72
	v_lshlrev_b32_e32 v104, 16, v104
	v_fmac_f32_e32 v24, v184, v72
	v_mul_f32_e32 v24, v24, v104
	s_waitcnt vmcnt(44)
	v_lshlrev_b32_e32 v73, 16, v73
	v_lshlrev_b32_e32 v105, 16, v105
	v_fmac_f32_e32 v25, v184, v73
	v_mul_f32_e32 v25, v25, v105
	v_cvt_pk_bf16_f32 v72, v24, v25
	v_lshrrev_b32_e32 v73, 16, v72
	s_waitcnt vmcnt(42)
	v_lshlrev_b32_e32 v74, 16, v74
	v_lshlrev_b32_e32 v106, 16, v106
	v_fmac_f32_e32 v26, v184, v74
	v_mul_f32_e32 v26, v26, v106
	s_waitcnt vmcnt(40)
	v_lshlrev_b32_e32 v75, 16, v75
	v_lshlrev_b32_e32 v107, 16, v107
	v_fmac_f32_e32 v27, v184, v75
	v_mul_f32_e32 v27, v27, v107
	v_cvt_pk_bf16_f32 v74, v26, v27
	v_lshrrev_b32_e32 v75, 16, v74
	s_waitcnt vmcnt(38)
	v_lshlrev_b32_e32 v76, 16, v76
	v_lshlrev_b32_e32 v108, 16, v108
	v_fmac_f32_e32 v28, v184, v76
	v_mul_f32_e32 v28, v28, v108
	s_waitcnt vmcnt(36)
	v_lshlrev_b32_e32 v77, 16, v77
	v_lshlrev_b32_e32 v109, 16, v109
	v_fmac_f32_e32 v29, v184, v77
	v_mul_f32_e32 v29, v29, v109
	v_cvt_pk_bf16_f32 v76, v28, v29
	v_lshrrev_b32_e32 v77, 16, v76
	s_waitcnt vmcnt(34)
	v_lshlrev_b32_e32 v78, 16, v78
	v_lshlrev_b32_e32 v110, 16, v110
	v_fmac_f32_e32 v30, v184, v78
	v_mul_f32_e32 v30, v30, v110
	s_waitcnt vmcnt(32)
	v_lshlrev_b32_e32 v79, 16, v79
	v_lshlrev_b32_e32 v111, 16, v111
	v_fmac_f32_e32 v31, v184, v79
	v_mul_f32_e32 v31, v31, v111
	v_cvt_pk_bf16_f32 v78, v30, v31
	v_lshrrev_b32_e32 v79, 16, v78
	s_waitcnt vmcnt(30)
	v_lshlrev_b32_e32 v80, 16, v80
	v_lshlrev_b32_e32 v112, 16, v112
	v_fmac_f32_e32 v0, v184, v80
	v_mul_f32_e32 v0, v0, v112
	s_waitcnt vmcnt(28)
	v_lshlrev_b32_e32 v81, 16, v81
	v_lshlrev_b32_e32 v113, 16, v113
	v_fmac_f32_e32 v1, v184, v81
	v_mul_f32_e32 v1, v1, v113
	v_cvt_pk_bf16_f32 v80, v0, v1
	v_lshrrev_b32_e32 v81, 16, v80
	s_waitcnt vmcnt(26)
	v_lshlrev_b32_e32 v82, 16, v82
	v_lshlrev_b32_e32 v114, 16, v114
	v_fmac_f32_e32 v2, v184, v82
	v_mul_f32_e32 v2, v2, v114
	s_waitcnt vmcnt(24)
	v_lshlrev_b32_e32 v83, 16, v83
	v_lshlrev_b32_e32 v115, 16, v115
	v_fmac_f32_e32 v3, v184, v83
	v_mul_f32_e32 v3, v3, v115
	v_cvt_pk_bf16_f32 v82, v2, v3
	v_lshrrev_b32_e32 v83, 16, v82
	s_waitcnt vmcnt(22)
	v_lshlrev_b32_e32 v84, 16, v84
	v_lshlrev_b32_e32 v116, 16, v116
	v_fmac_f32_e32 v4, v184, v84
	v_mul_f32_e32 v4, v4, v116
	s_waitcnt vmcnt(20)
	v_lshlrev_b32_e32 v85, 16, v85
	v_lshlrev_b32_e32 v117, 16, v117
	v_fmac_f32_e32 v5, v184, v85
	v_mul_f32_e32 v5, v5, v117
	v_cvt_pk_bf16_f32 v84, v4, v5
	v_lshrrev_b32_e32 v85, 16, v84
	s_waitcnt vmcnt(18)
	v_lshlrev_b32_e32 v86, 16, v86
	v_lshlrev_b32_e32 v118, 16, v118
	v_fmac_f32_e32 v6, v184, v86
	v_mul_f32_e32 v6, v6, v118
	s_waitcnt vmcnt(16)
	v_lshlrev_b32_e32 v87, 16, v87
	v_lshlrev_b32_e32 v119, 16, v119
	v_fmac_f32_e32 v7, v184, v87
	v_mul_f32_e32 v7, v7, v119
	v_cvt_pk_bf16_f32 v86, v6, v7
	v_lshrrev_b32_e32 v87, 16, v86
	s_waitcnt vmcnt(14)
	v_lshlrev_b32_e32 v88, 16, v88
	v_lshlrev_b32_e32 v120, 16, v120
	v_fmac_f32_e32 v8, v184, v88
	v_mul_f32_e32 v8, v8, v120
	s_waitcnt vmcnt(12)
	v_lshlrev_b32_e32 v89, 16, v89
	v_lshlrev_b32_e32 v121, 16, v121
	v_fmac_f32_e32 v9, v184, v89
	v_mul_f32_e32 v9, v9, v121
	v_cvt_pk_bf16_f32 v88, v8, v9
	v_lshrrev_b32_e32 v89, 16, v88
	s_waitcnt vmcnt(10)
	v_lshlrev_b32_e32 v90, 16, v90
	v_lshlrev_b32_e32 v122, 16, v122
	v_fmac_f32_e32 v10, v184, v90
	v_mul_f32_e32 v10, v10, v122
	s_waitcnt vmcnt(8)
	v_lshlrev_b32_e32 v91, 16, v91
	v_lshlrev_b32_e32 v123, 16, v123
	v_fmac_f32_e32 v11, v184, v91
	v_mul_f32_e32 v11, v11, v123
	v_cvt_pk_bf16_f32 v90, v10, v11
	v_lshrrev_b32_e32 v91, 16, v90
	s_waitcnt vmcnt(6)
	v_lshlrev_b32_e32 v92, 16, v92
	v_lshlrev_b32_e32 v124, 16, v124
	v_fmac_f32_e32 v12, v184, v92
	v_mul_f32_e32 v12, v12, v124
	s_waitcnt vmcnt(4)
	v_lshlrev_b32_e32 v93, 16, v93
	v_lshlrev_b32_e32 v125, 16, v125
	v_fmac_f32_e32 v13, v184, v93
	v_mul_f32_e32 v13, v13, v125
	v_cvt_pk_bf16_f32 v92, v12, v13
	v_lshrrev_b32_e32 v93, 16, v92
	s_waitcnt vmcnt(2)
; __device__ __forceinline__ unsigned pk2(float lo, float hi) { unsigned r; asm("v_cvt_pk_bf16_f32 %0, %1, %2" : "=v"(r) : "v"(lo), "v"(hi)); return r; }
; __device__ __forceinline__ float bf2f(bf16_t b) { return __uint_as_float(((unsigned)b) << 16); }
; template <int EPI>
; __device__ __forceinline__ void hy_conv(const Args& a, int L, int c, const bf16_t* U, LAS unsigned char* lds) {
;     ...
; #pragma unroll
;         for (int tt = 0; tt < 4; ++tt)
; #pragma unroll
;             for (int i = 0; i < 16; ++i) {
;                 const int bb = (i & 3) + 8 * (i >> 2) + 4 * h, t = 32 * (tb + tt) + n;
;                 const size_t tok = (size_t)bb * SEQ + t;
;                 if (EPI == 0) {
;                     const float v = bf2f(UC[(size_t)c * MTOK + tok]), x1 = bf2f(UC[((size_t)256 + c) * MTOK + tok]);
;                     const float z = x1 * (acc[tt][i] + dbias * v);
;                     Z[tok] = (bf16_t)(pk2(z, 0.f) & 0xffffu);
;                 } else {
;                     const float zz = bf2f(Z[tok]), x2 = bf2f(UC[((size_t)512 + c) * MTOK + tok]);
;                     const float o = x2 * (acc[tt][i] + dbias * zz);
;                     MIX[tok * DM + 384 + c] = (bf16_t)(pk2(o, 0.f) & 0xffffu);
;                 }
;             }
;     }
; }
	v_lshlrev_b32_e32 v94, 16, v94
	v_lshlrev_b32_e32 v126, 16, v126
	v_fmac_f32_e32 v14, v184, v94
	v_mul_f32_e32 v14, v14, v126
	s_waitcnt vmcnt(0)
	v_lshlrev_b32_e32 v95, 16, v95
	v_lshlrev_b32_e32 v127, 16, v127
	v_fmac_f32_e32 v15, v184, v95
	v_mul_f32_e32 v15, v15, v127
	v_cvt_pk_bf16_f32 v94, v14, v15
	v_lshrrev_b32_e32 v95, 16, v94
	v_add_u32_e32 v141, 0x0, v143
	global_store_short v141, v64, s[20:21] offset:128
	v_add_u32_e32 v141, 0x1000, v143
	global_store_short v141, v65, s[20:21] offset:128
	v_add_u32_e32 v141, 0x2000, v143
	global_store_short v141, v66, s[20:21] offset:128
	v_add_u32_e32 v141, 0x3000, v143
	global_store_short v141, v67, s[20:21] offset:128
	v_add_u32_e32 v141, 0x8000, v143
	global_store_short v141, v68, s[20:21] offset:128
	v_add_u32_e32 v141, 0x9000, v143
	global_store_short v141, v69, s[20:21] offset:128
	v_add_u32_e32 v141, 0xa000, v143
	global_store_short v141, v70, s[20:21] offset:128
	v_add_u32_e32 v141, 0xb000, v143
	global_store_short v141, v71, s[20:21] offset:128
	v_add_u32_e32 v141, 0x10000, v143
	global_store_short v141, v72, s[20:21] offset:128
	v_add_u32_e32 v141, 0x11000, v143
	global_store_short v141, v73, s[20:21] offset:128
	v_add_u32_e32 v141, 0x12000, v143
	global_store_short v141, v74, s[20:21] offset:128
	v_add_u32_e32 v141, 0x13000, v143
	global_store_short v141, v75, s[20:21] offset:128
	v_add_u32_e32 v141, 0x18000, v143
	global_store_short v141, v76, s[20:21] offset:128
	v_add_u32_e32 v141, 0x19000, v143
	global_store_short v141, v77, s[20:21] offset:128
	v_add_u32_e32 v141, 0x1a000, v143
	global_store_short v141, v78, s[20:21] offset:128
	v_add_u32_e32 v141, 0x1b000, v143
	global_store_short v141, v79, s[20:21] offset:128
	v_add_u32_e32 v141, 0x0, v143
	global_store_short v141, v80, s[20:21] offset:192
	v_add_u32_e32 v141, 0x1000, v143
	global_store_short v141, v81, s[20:21] offset:192
	v_add_u32_e32 v141, 0x2000, v143
	global_store_short v141, v82, s[20:21] offset:192
	v_add_u32_e32 v141, 0x3000, v143
	global_store_short v141, v83, s[20:21] offset:192
	v_add_u32_e32 v141, 0x8000, v143
	global_store_short v141, v84, s[20:21] offset:192
	v_add_u32_e32 v141, 0x9000, v143
	global_store_short v141, v85, s[20:21] offset:192
	v_add_u32_e32 v141, 0xa000, v143
	global_store_short v141, v86, s[20:21] offset:192
	v_add_u32_e32 v141, 0xb000, v143
	global_store_short v141, v87, s[20:21] offset:192
	v_add_u32_e32 v141, 0x10000, v143
	global_store_short v141, v88, s[20:21] offset:192
	v_add_u32_e32 v141, 0x11000, v143
	global_store_short v141, v89, s[20:21] offset:192
	v_add_u32_e32 v141, 0x12000, v143
	global_store_short v141, v90, s[20:21] offset:192
	v_add_u32_e32 v141, 0x13000, v143
	global_store_short v141, v91, s[20:21] offset:192
	v_add_u32_e32 v141, 0x18000, v143
	global_store_short v141, v92, s[20:21] offset:192
	v_add_u32_e32 v141, 0x19000, v143
	global_store_short v141, v93, s[20:21] offset:192
	v_add_u32_e32 v141, 0x1a000, v143
	global_store_short v141, v94, s[20:21] offset:192
	v_add_u32_e32 v141, 0x1b000, v143
	global_store_short v141, v95, s[20:21] offset:192
	s_cmp_eq_u32 s26, 16
	s_cbranch_scc1 .Lhc0_done
	v_mov_b32_e32 v0, 0
	v_mov_b32_e32 v1, 0
	v_mov_b32_e32 v2, 0
	v_mov_b32_e32 v3, 0
	v_mov_b32_e32 v4, 0
	v_mov_b32_e32 v5, 0
	v_mov_b32_e32 v6, 0
	v_mov_b32_e32 v7, 0
	v_mov_b32_e32 v8, 0
	v_mov_b32_e32 v9, 0
	v_mov_b32_e32 v10, 0
	v_mov_b32_e32 v11, 0
	v_mov_b32_e32 v12, 0
	v_mov_b32_e32 v13, 0
	v_mov_b32_e32 v14, 0
	v_mov_b32_e32 v15, 0
	v_mov_b32_e32 v16, 0
	v_mov_b32_e32 v17, 0
	v_mov_b32_e32 v18, 0
	v_mov_b32_e32 v19, 0
	v_mov_b32_e32 v20, 0
	v_mov_b32_e32 v21, 0
	v_mov_b32_e32 v22, 0
	v_mov_b32_e32 v23, 0
	v_mov_b32_e32 v24, 0
	v_mov_b32_e32 v25, 0
	v_mov_b32_e32 v26, 0
	v_mov_b32_e32 v27, 0
	v_mov_b32_e32 v28, 0
	v_mov_b32_e32 v29, 0
	v_mov_b32_e32 v30, 0
	v_mov_b32_e32 v31, 0
	v_mov_b32_e32 v32, 0
	v_mov_b32_e32 v33, 0
	v_mov_b32_e32 v34, 0
	v_mov_b32_e32 v35, 0
	v_mov_b32_e32 v36, 0
	v_mov_b32_e32 v37, 0
	v_mov_b32_e32 v38, 0
	v_mov_b32_e32 v39, 0
	v_mov_b32_e32 v40, 0
	v_mov_b32_e32 v41, 0
	v_mov_b32_e32 v42, 0
	v_mov_b32_e32 v43, 0
	v_mov_b32_e32 v44, 0
	v_mov_b32_e32 v45, 0
	v_mov_b32_e32 v46, 0
	v_mov_b32_e32 v47, 0
	v_mov_b32_e32 v48, 0
	v_mov_b32_e32 v49, 0
	v_mov_b32_e32 v50, 0
	v_mov_b32_e32 v51, 0
	v_mov_b32_e32 v52, 0
	v_mov_b32_e32 v53, 0
	v_mov_b32_e32 v54, 0
	v_mov_b32_e32 v55, 0
	v_mov_b32_e32 v56, 0
	v_mov_b32_e32 v57, 0
	v_mov_b32_e32 v58, 0
	v_mov_b32_e32 v59, 0
	v_mov_b32_e32 v60, 0
	v_mov_b32_e32 v61, 0
	v_mov_b32_e32 v62, 0
	v_mov_b32_e32 v63, 0
	v_add_u32_e32 v214, 0xffffff00, v212
	s_branch .Lhc0_blk

; #define LAS __attribute__((address_space(3)))
; __device__ __forceinline__ int tidx() { int t = threadIdx.x; asm volatile("" : "+v"(t)); return t; }
; template <int EPI>
; __device__ __forceinline__ void hy_conv(const Args& a, int L, int c, const bf16_t* U, LAS unsigned char* lds) {
;     const int tid = tidx(), wid = tid >> 6, lane = tid & 63, n = lane & 31, h = lane >> 5;
;     const bf16_t* UC = (const bf16_t*)(a.ws + OFF_UC);
;     bf16_t* Z = (bf16_t*)(a.ws + OFF_Z) + (size_t)c * MTOK;
;     bf16_t* MIX = (bf16_t*)(a.ws + WS_MIX);
;     const float dbias = a.in[18][L * 512 + EPI * 256 + c];
;     const bf16_t* urow = U + (size_t)n * SEQ + 8 * h;
;     LAS const unsigned char* fbase = lds + (n & 7) * HY_CP;
;     const int foff = 8 * h - (n & ~7);
; #pragma unroll 1
;     for (int blk = 0; blk < 2; ++blk) {
;         const int tb = 8 * wid + 4 * blk;
;         f32x16 acc[4];
; #pragma unroll
;         for (int tt = 0; tt < 4; ++tt)
; #pragma unroll
;             for (int i = 0; i < 16; ++i) acc[tt][i] = 0.f;
;         bf16x8 an[4];
; #pragma unroll
;         for (int k = 0; k < 4; ++k) an[k] = *(const bf16x8*)(urow + 16 * k);
; #pragma unroll 1
.LBB0_206:
	s_or_b64 exec, exec, s[22:23]
	v_mov_b32_e32 v2, v225
	s_waitcnt lgkmcnt(0)
	s_barrier
	global_load_dword v178, v155, s[0:1] offset:1024
	s_add_u32 s0, s41, s2
	s_addc_u32 s1, s42, s3
	s_add_u32 s20, s66, s2
	s_addc_u32 s21, s67, s3
	s_add_u32 s2, s45, s2
	s_addc_u32 s3, s46, s3
	v_and_b32_e32 v140, 31, v225
	v_bfe_u32 v141, v225, 5, 1
	v_lshrrev_b32_e32 v142, 6, v225
	v_and_b32_e32 v143, 15, v140
	v_xor_b32_e32 v143, v141, v143
	v_lshlrev_b32_e32 v143, 4, v143
	v_lshl_or_b32 v210, v140, 9, v143
	v_and_b32_e32 v143, 7, v140
	v_mul_u32_u24_e32 v211, 0x2040, v143
	v_lshrrev_b32_e32 v143, 3, v140
	v_sub_u32_e32 v143, v141, v143
	v_lshlrev_b32_e32 v143, 4, v143
	v_lshlrev_b32_e32 v144, 9, v142
	v_sub_u32_e32 v212, v143, v144
	v_lshl_add_u32 v143, v142, 2, v141
	v_and_b32_e32 v144, 15, v143
	v_xor_b32_e32 v144, v140, v144
	v_lshlrev_b32_e32 v144, 4, v144
	v_lshl_or_b32 v208, v143, 12, v144
	v_add_u32_e32 v143, 2, v143
	v_and_b32_e32 v144, 15, v143
	v_xor_b32_e32 v144, v140, v144
	v_lshlrev_b32_e32 v144, 4, v144
	v_lshl_or_b32 v209, v143, 12, v144
	v_readfirstlane_b32 s31, v142
	v_mov_b32_e32 v214, v212
	s_lshl_b32 s31, s31, 11
	v_mov_b32_e32 v0, 0
	v_mov_b32_e32 v1, 0
	v_mov_b32_e32 v2, 0
	v_mov_b32_e32 v3, 0
	v_mov_b32_e32 v4, 0
	v_mov_b32_e32 v5, 0
	v_mov_b32_e32 v6, 0
	v_mov_b32_e32 v7, 0
	v_mov_b32_e32 v8, 0
	v_mov_b32_e32 v9, 0
	v_mov_b32_e32 v10, 0
	v_mov_b32_e32 v11, 0
	v_mov_b32_e32 v12, 0
	v_mov_b32_e32 v13, 0
	v_mov_b32_e32 v14, 0
	v_mov_b32_e32 v15, 0
	v_mov_b32_e32 v16, 0
	v_mov_b32_e32 v17, 0
	v_mov_b32_e32 v18, 0
	v_mov_b32_e32 v19, 0
	v_mov_b32_e32 v20, 0
	v_mov_b32_e32 v21, 0
	v_mov_b32_e32 v22, 0
	v_mov_b32_e32 v23, 0
	v_mov_b32_e32 v24, 0
	v_mov_b32_e32 v25, 0
	v_mov_b32_e32 v26, 0
	v_mov_b32_e32 v27, 0
	v_mov_b32_e32 v28, 0
	v_mov_b32_e32 v29, 0
	v_mov_b32_e32 v30, 0
	v_mov_b32_e32 v31, 0
	v_mov_b32_e32 v32, 0
	v_mov_b32_e32 v33, 0
	v_mov_b32_e32 v34, 0
	v_mov_b32_e32 v35, 0
	v_mov_b32_e32 v36, 0
	v_mov_b32_e32 v37, 0
	v_mov_b32_e32 v38, 0
	v_mov_b32_e32 v39, 0
	v_mov_b32_e32 v40, 0
	v_mov_b32_e32 v41, 0
	v_mov_b32_e32 v42, 0
	v_mov_b32_e32 v43, 0
	v_mov_b32_e32 v44, 0
	v_mov_b32_e32 v45, 0
	v_mov_b32_e32 v46, 0
	v_mov_b32_e32 v47, 0
	v_mov_b32_e32 v48, 0
	v_mov_b32_e32 v49, 0
	v_mov_b32_e32 v50, 0
	v_mov_b32_e32 v51, 0
	v_mov_b32_e32 v52, 0
	v_mov_b32_e32 v53, 0
	v_mov_b32_e32 v54, 0
	v_mov_b32_e32 v55, 0
	v_mov_b32_e32 v56, 0
	v_mov_b32_e32 v57, 0
	v_mov_b32_e32 v58, 0
	v_mov_b32_e32 v59, 0
	v_mov_b32_e32 v60, 0
	v_mov_b32_e32 v61, 0
	v_mov_b32_e32 v62, 0
	v_mov_b32_e32 v63, 0
	s_mov_b32 s30, 0x18000
	s_add_i32 m0, s30, s31
	s_nop 0
	global_load_lds_dwordx4 v208, s[0:1]
	s_nop 0
	s_add_i32 m0, m0, 0x400
	s_nop 0
	global_load_lds_dwordx4 v209, s[0:1]
	s_add_u32 s28, s0, 0x200
	s_addc_u32 s29, s1, 0
	s_mov_b32 s30, 0x1c000
	s_add_i32 m0, s30, s31
	s_nop 0
	global_load_lds_dwordx4 v208, s[28:29]
	s_nop 0
	s_add_i32 m0, m0, 0x400
	s_nop 0
	global_load_lds_dwordx4 v209, s[28:29]
	s_add_u32 s28, s0, 0x400
	s_addc_u32 s29, s1, 0
	s_mov_b32 s30, 0x20000
	s_add_i32 m0, s30, s31
	s_nop 0
	global_load_lds_dwordx4 v208, s[28:29]
	s_nop 0
	s_add_i32 m0, m0, 0x400
	s_nop 0
	global_load_lds_dwordx4 v209, s[28:29]
	s_mov_b32 s26, 0
	s_mov_b32 s27, 0x18000
	v_add_u32_e32 v213, s27, v210
	s_waitcnt vmcnt(4)
	s_barrier

; #define LAS __attribute__((address_space(3)))
; template <int EPI>
; __device__ __forceinline__ void hy_conv(const Args& a, int L, int c, const bf16_t* U, LAS unsigned char* lds) {
;     ...
;         for (int s0 = 0; s0 < SEQ; s0 += 64) {
;             bf16x8 ac[4];
; #pragma unroll
;             for (int k = 0; k < 4; ++k) ac[k] = an[k];
;             if (s0 + 64 < SEQ) {
; #pragma unroll
;                 for (int k = 0; k < 4; ++k) an[k] = *(const bf16x8*)(urow + s0 + 64 + 16 * k);
;             }
;             bf16x8 bfr[10];
;             const int D0 = s0 - 32 * tb + foff;
; #pragma unroll
;             for (int d = 0; d < 10; ++d) { const int x = (D0 + 16 * (d - 6)) & 4095; bfr[d] = *(const LAS bf16x8*)(fbase + x * 2); }
.Lhc1_wdone:
	s_barrier
	s_add_u32 s30, s26, 3
	s_cmp_ge_u32 s30, 16
	s_cbranch_scc1 .Lhc1_nodma
	s_and_b32 s28, s30, 7
	s_lshl_b32 s28, s28, 9
	s_add_u32 s28, s0, s28
	s_addc_u32 s29, s1, 0
	s_add_i32 m0, s27, s31
	s_nop 0
	global_load_lds_dwordx4 v208, s[28:29]
	s_nop 0
	s_add_i32 m0, m0, 0x400
	s_nop 0
	global_load_lds_dwordx4 v209, s[28:29]

; __device__ __forceinline__ unsigned pk2(float lo, float hi) { unsigned r; asm("v_cvt_pk_bf16_f32 %0, %1, %2" : "=v"(r) : "v"(lo), "v"(hi)); return r; }
; __device__ __forceinline__ float bf2f(bf16_t b) { return __uint_as_float(((unsigned)b) << 16); }
; template <int EPI>
; __device__ __forceinline__ void hy_conv(const Args& a, int L, int c, const bf16_t* U, LAS unsigned char* lds) {
;     ...
; #pragma unroll
;         for (int tt = 0; tt < 4; ++tt)
; #pragma unroll
;             for (int i = 0; i < 16; ++i) {
;                 const int bb = (i & 3) + 8 * (i >> 2) + 4 * h, t = 32 * (tb + tt) + n;
;                 const size_t tok = (size_t)bb * SEQ + t;
;                 if (EPI == 0) {
;                     const float v = bf2f(UC[(size_t)c * MTOK + tok]), x1 = bf2f(UC[((size_t)256 + c) * MTOK + tok]);
;                     const float z = x1 * (acc[tt][i] + dbias * v);
;                     Z[tok] = (bf16_t)(pk2(z, 0.f) & 0xffffu);
;                 } else {
;                     const float zz = bf2f(Z[tok]), x2 = bf2f(UC[((size_t)512 + c) * MTOK + tok]);
;                     const float o = x2 * (acc[tt][i] + dbias * zz);
;                     MIX[tok * DM + 384 + c] = (bf16_t)(pk2(o, 0.f) & 0xffffu);
;                 }
.Lhc1_last:
	v_mfma_f32_32x32x16_bf16 v[48:63], v[80:83], v[196:199], v[48:63]
	v_mfma_f32_32x32x16_bf16 v[32:47], v[80:83], v[188:191], v[32:47]
	v_mfma_f32_32x32x16_bf16 v[16:31], v[80:83], v[144:147], v[16:31]
	v_mfma_f32_32x32x16_bf16 v[0:15], v[80:83], v[136:139], v[0:15]
	v_mfma_f32_32x32x16_bf16 v[48:63], v[84:87], v[200:203], v[48:63]
	v_mfma_f32_32x32x16_bf16 v[32:47], v[84:87], v[192:195], v[32:47]
	v_mfma_f32_32x32x16_bf16 v[16:31], v[84:87], v[148:151], v[16:31]
	v_mfma_f32_32x32x16_bf16 v[0:15], v[84:87], v[140:143], v[0:15]
	v_mfma_f32_32x32x16_bf16 v[48:63], v[88:91], v[204:207], v[48:63]
	v_mfma_f32_32x32x16_bf16 v[32:47], v[88:91], v[196:199], v[32:47]
	v_mfma_f32_32x32x16_bf16 v[16:31], v[88:91], v[188:191], v[16:31]
	v_mfma_f32_32x32x16_bf16 v[0:15], v[88:91], v[144:147], v[0:15]
	v_mfma_f32_32x32x16_bf16 v[48:63], v[92:95], v[216:219], v[48:63]
	v_mfma_f32_32x32x16_bf16 v[32:47], v[92:95], v[200:203], v[32:47]
	v_mfma_f32_32x32x16_bf16 v[16:31], v[92:95], v[192:195], v[16:31]
	v_mfma_f32_32x32x16_bf16 v[0:15], v[92:95], v[148:151], v[0:15]
	v_mov_b32_e32 v213, v215
	s_add_u32 s26, s26, 1
	s_lshr_b32 s30, s26, 3
	s_sub_u32 s30, s30, 1
	s_lshl_b32 s30, s30, 2
	v_and_b32_e32 v140, 31, v225
	v_bfe_u32 v141, v225, 5, 1
	v_lshrrev_b32_e32 v142, 6, v225
	v_lshlrev_b32_e32 v143, 1, v140
	v_lshl_or_b32 v143, v141, 14, v143
	v_lshl_or_b32 v143, v142, 9, v143
	s_lshl_b32 s28, s30, 6
	v_or_b32_e32 v143, s28, v143
	v_lshlrev_b32_e32 v144, 11, v140
	v_lshl_or_b32 v144, v141, 24, v144
	v_lshl_or_b32 v144, v142, 19, v144
	s_lshl_b32 s28, s30, 16
	v_or_b32_e32 v144, s28, v144
	v_add_u32_e32 v141, 0x0, v143
	global_load_ushort v64, v141, s[0:1] offset:0
	global_load_ushort v96, v141, s[2:3] offset:0
	v_add_u32_e32 v141, 0x1000, v143
	global_load_ushort v65, v141, s[0:1] offset:0
	global_load_ushort v97, v141, s[2:3] offset:0
	v_add_u32_e32 v141, 0x2000, v143
	global_load_ushort v66, v141, s[0:1] offset:0
	global_load_ushort v98, v141, s[2:3] offset:0
	v_add_u32_e32 v141, 0x3000, v143
	global_load_ushort v67, v141, s[0:1] offset:0
	global_load_ushort v99, v141, s[2:3] offset:0
	v_add_u32_e32 v141, 0x8000, v143
	global_load_ushort v68, v141, s[0:1] offset:0
	global_load_ushort v100, v141, s[2:3] offset:0
	v_add_u32_e32 v141, 0x9000, v143
	global_load_ushort v69, v141, s[0:1] offset:0
	global_load_ushort v101, v141, s[2:3] offset:0
	v_add_u32_e32 v141, 0xa000, v143
	global_load_ushort v70, v141, s[0:1] offset:0
	global_load_ushort v102, v141, s[2:3] offset:0
	v_add_u32_e32 v141, 0xb000, v143
	global_load_ushort v71, v141, s[0:1] offset:0
	global_load_ushort v103, v141, s[2:3] offset:0
	v_add_u32_e32 v141, 0x10000, v143
	global_load_ushort v72, v141, s[0:1] offset:0
	global_load_ushort v104, v141, s[2:3] offset:0
	v_add_u32_e32 v141, 0x11000, v143
	global_load_ushort v73, v141, s[0:1] offset:0
	global_load_ushort v105, v141, s[2:3] offset:0
	v_add_u32_e32 v141, 0x12000, v143
	global_load_ushort v74, v141, s[0:1] offset:0
	global_load_ushort v106, v141, s[2:3] offset:0
	v_add_u32_e32 v141, 0x13000, v143
	global_load_ushort v75, v141, s[0:1] offset:0
	global_load_ushort v107, v141, s[2:3] offset:0
	v_add_u32_e32 v141, 0x18000, v143
	global_load_ushort v76, v141, s[0:1] offset:0
	global_load_ushort v108, v141, s[2:3] offset:0
	v_add_u32_e32 v141, 0x19000, v143
	global_load_ushort v77, v141, s[0:1] offset:0
	global_load_ushort v109, v141, s[2:3] offset:0
	v_add_u32_e32 v141, 0x1a000, v143
	global_load_ushort v78, v141, s[0:1] offset:0
	global_load_ushort v110, v141, s[2:3] offset:0
	v_add_u32_e32 v141, 0x1b000, v143
	global_load_ushort v79, v141, s[0:1] offset:0
	global_load_ushort v111, v141, s[2:3] offset:0
	v_add_u32_e32 v141, 0x0, v143
	global_load_ushort v80, v141, s[0:1] offset:64
	global_load_ushort v112, v141, s[2:3] offset:64
	v_add_u32_e32 v141, 0x1000, v143
	global_load_ushort v81, v141, s[0:1] offset:64
	global_load_ushort v113, v141, s[2:3] offset:64
	v_add_u32_e32 v141, 0x2000, v143
	global_load_ushort v82, v141, s[0:1] offset:64
	global_load_ushort v114, v141, s[2:3] offset:64
	v_add_u32_e32 v141, 0x3000, v143
	global_load_ushort v83, v141, s[0:1] offset:64
	global_load_ushort v115, v141, s[2:3] offset:64
	v_add_u32_e32 v141, 0x8000, v143
	global_load_ushort v84, v141, s[0:1] offset:64
	global_load_ushort v116, v141, s[2:3] offset:64
	v_add_u32_e32 v141, 0x9000, v143
	global_load_ushort v85, v141, s[0:1] offset:64
	global_load_ushort v117, v141, s[2:3] offset:64
	v_add_u32_e32 v141, 0xa000, v143
	global_load_ushort v86, v141, s[0:1] offset:64
	global_load_ushort v118, v141, s[2:3] offset:64
	v_add_u32_e32 v141, 0xb000, v143
	global_load_ushort v87, v141, s[0:1] offset:64
	global_load_ushort v119, v141, s[2:3] offset:64
	v_add_u32_e32 v141, 0x10000, v143
	global_load_ushort v88, v141, s[0:1] offset:64
	global_load_ushort v120, v141, s[2:3] offset:64
	v_add_u32_e32 v141, 0x11000, v143
	global_load_ushort v89, v141, s[0:1] offset:64
	global_load_ushort v121, v141, s[2:3] offset:64
	v_add_u32_e32 v141, 0x12000, v143
	global_load_ushort v90, v141, s[0:1] offset:64
	global_load_ushort v122, v141, s[2:3] offset:64
	v_add_u32_e32 v141, 0x13000, v143
	global_load_ushort v91, v141, s[0:1] offset:64
	global_load_ushort v123, v141, s[2:3] offset:64
	v_add_u32_e32 v141, 0x18000, v143
	global_load_ushort v92, v141, s[0:1] offset:64
	global_load_ushort v124, v141, s[2:3] offset:64
	v_add_u32_e32 v141, 0x19000, v143
	global_load_ushort v93, v141, s[0:1] offset:64
	global_load_ushort v125, v141, s[2:3] offset:64
	v_add_u32_e32 v141, 0x1a000, v143
	global_load_ushort v94, v141, s[0:1] offset:64
	global_load_ushort v126, v141, s[2:3] offset:64
	v_add_u32_e32 v141, 0x1b000, v143
	global_load_ushort v95, v141, s[0:1] offset:64
	global_load_ushort v127, v141, s[2:3] offset:64
	s_waitcnt vmcnt(62)
; __device__ __forceinline__ unsigned pk2(float lo, float hi) { unsigned r; asm("v_cvt_pk_bf16_f32 %0, %1, %2" : "=v"(r) : "v"(lo), "v"(hi)); return r; }
; __device__ __forceinline__ float bf2f(bf16_t b) { return __uint_as_float(((unsigned)b) << 16); }
; template <int EPI>
; __device__ __forceinline__ void hy_conv(const Args& a, int L, int c, const bf16_t* U, LAS unsigned char* lds) {
;     ...
; #pragma unroll
;         for (int tt = 0; tt < 4; ++tt)
; #pragma unroll
;             for (int i = 0; i < 16; ++i) {
;                 const int bb = (i & 3) + 8 * (i >> 2) + 4 * h, t = 32 * (tb + tt) + n;
;                 const size_t tok = (size_t)bb * SEQ + t;
;                 if (EPI == 0) {
;                     const float v = bf2f(UC[(size_t)c * MTOK + tok]), x1 = bf2f(UC[((size_t)256 + c) * MTOK + tok]);
;                     const float z = x1 * (acc[tt][i] + dbias * v);
;                     Z[tok] = (bf16_t)(pk2(z, 0.f) & 0xffffu);
;                 } else {
;                     const float zz = bf2f(Z[tok]), x2 = bf2f(UC[((size_t)512 + c) * MTOK + tok]);
;                     const float o = x2 * (acc[tt][i] + dbias * zz);
;                     MIX[tok * DM + 384 + c] = (bf16_t)(pk2(o, 0.f) & 0xffffu);
;                 }
;             }
	v_lshlrev_b32_e32 v64, 16, v64
	v_lshlrev_b32_e32 v96, 16, v96
	v_fmac_f32_e32 v48, v178, v64
	v_mul_f32_e32 v48, v48, v96
	s_waitcnt vmcnt(60)
	v_lshlrev_b32_e32 v65, 16, v65
	v_lshlrev_b32_e32 v97, 16, v97
	v_fmac_f32_e32 v49, v178, v65
	v_mul_f32_e32 v49, v49, v97
	v_cvt_pk_bf16_f32 v64, v48, v49
	v_lshrrev_b32_e32 v65, 16, v64
	s_waitcnt vmcnt(58)
	v_lshlrev_b32_e32 v66, 16, v66
	v_lshlrev_b32_e32 v98, 16, v98
	v_fmac_f32_e32 v50, v178, v66
	v_mul_f32_e32 v50, v50, v98
	s_waitcnt vmcnt(56)
	v_lshlrev_b32_e32 v67, 16, v67
	v_lshlrev_b32_e32 v99, 16, v99
	v_fmac_f32_e32 v51, v178, v67
	v_mul_f32_e32 v51, v51, v99
	v_cvt_pk_bf16_f32 v66, v50, v51
	v_lshrrev_b32_e32 v67, 16, v66
	s_waitcnt vmcnt(54)
	v_lshlrev_b32_e32 v68, 16, v68
	v_lshlrev_b32_e32 v100, 16, v100
	v_fmac_f32_e32 v52, v178, v68
	v_mul_f32_e32 v52, v52, v100
	s_waitcnt vmcnt(52)
	v_lshlrev_b32_e32 v69, 16, v69
	v_lshlrev_b32_e32 v101, 16, v101
	v_fmac_f32_e32 v53, v178, v69
	v_mul_f32_e32 v53, v53, v101
	v_cvt_pk_bf16_f32 v68, v52, v53
	v_lshrrev_b32_e32 v69, 16, v68
	s_waitcnt vmcnt(50)
	v_lshlrev_b32_e32 v70, 16, v70
	v_lshlrev_b32_e32 v102, 16, v102
	v_fmac_f32_e32 v54, v178, v70
	v_mul_f32_e32 v54, v54, v102
	s_waitcnt vmcnt(48)
	v_lshlrev_b32_e32 v71, 16, v71
	v_lshlrev_b32_e32 v103, 16, v103
	v_fmac_f32_e32 v55, v178, v71
	v_mul_f32_e32 v55, v55, v103
	v_cvt_pk_bf16_f32 v70, v54, v55
	v_lshrrev_b32_e32 v71, 16, v70
	s_waitcnt vmcnt(46)
	v_lshlrev_b32_e32 v72, 16, v72
	v_lshlrev_b32_e32 v104, 16, v104
	v_fmac_f32_e32 v56, v178, v72
	v_mul_f32_e32 v56, v56, v104
	s_waitcnt vmcnt(44)
	v_lshlrev_b32_e32 v73, 16, v73
	v_lshlrev_b32_e32 v105, 16, v105
	v_fmac_f32_e32 v57, v178, v73
	v_mul_f32_e32 v57, v57, v105
	v_cvt_pk_bf16_f32 v72, v56, v57
	v_lshrrev_b32_e32 v73, 16, v72
	s_waitcnt vmcnt(42)
	v_lshlrev_b32_e32 v74, 16, v74
	v_lshlrev_b32_e32 v106, 16, v106
	v_fmac_f32_e32 v58, v178, v74
	v_mul_f32_e32 v58, v58, v106
	s_waitcnt vmcnt(40)
	v_lshlrev_b32_e32 v75, 16, v75
	v_lshlrev_b32_e32 v107, 16, v107
	v_fmac_f32_e32 v59, v178, v75
	v_mul_f32_e32 v59, v59, v107
	v_cvt_pk_bf16_f32 v74, v58, v59
	v_lshrrev_b32_e32 v75, 16, v74
	s_waitcnt vmcnt(38)
	v_lshlrev_b32_e32 v76, 16, v76
	v_lshlrev_b32_e32 v108, 16, v108
	v_fmac_f32_e32 v60, v178, v76
	v_mul_f32_e32 v60, v60, v108
	s_waitcnt vmcnt(36)
	v_lshlrev_b32_e32 v77, 16, v77
	v_lshlrev_b32_e32 v109, 16, v109
	v_fmac_f32_e32 v61, v178, v77
	v_mul_f32_e32 v61, v61, v109
	v_cvt_pk_bf16_f32 v76, v60, v61
	v_lshrrev_b32_e32 v77, 16, v76
	s_waitcnt vmcnt(34)
	v_lshlrev_b32_e32 v78, 16, v78
	v_lshlrev_b32_e32 v110, 16, v110
	v_fmac_f32_e32 v62, v178, v78
	v_mul_f32_e32 v62, v62, v110
	s_waitcnt vmcnt(32)
	v_lshlrev_b32_e32 v79, 16, v79
	v_lshlrev_b32_e32 v111, 16, v111
	v_fmac_f32_e32 v63, v178, v79
	v_mul_f32_e32 v63, v63, v111
	v_cvt_pk_bf16_f32 v78, v62, v63
	v_lshrrev_b32_e32 v79, 16, v78
	s_waitcnt vmcnt(30)
	v_lshlrev_b32_e32 v80, 16, v80
	v_lshlrev_b32_e32 v112, 16, v112
	v_fmac_f32_e32 v32, v178, v80
	v_mul_f32_e32 v32, v32, v112
	s_waitcnt vmcnt(28)
	v_lshlrev_b32_e32 v81, 16, v81
	v_lshlrev_b32_e32 v113, 16, v113
	v_fmac_f32_e32 v33, v178, v81
	v_mul_f32_e32 v33, v33, v113
	v_cvt_pk_bf16_f32 v80, v32, v33
	v_lshrrev_b32_e32 v81, 16, v80
	s_waitcnt vmcnt(26)
	v_lshlrev_b32_e32 v82, 16, v82
	v_lshlrev_b32_e32 v114, 16, v114
	v_fmac_f32_e32 v34, v178, v82
	v_mul_f32_e32 v34, v34, v114
	s_waitcnt vmcnt(24)
	v_lshlrev_b32_e32 v83, 16, v83
	v_lshlrev_b32_e32 v115, 16, v115
	v_fmac_f32_e32 v35, v178, v83
	v_mul_f32_e32 v35, v35, v115
	v_cvt_pk_bf16_f32 v82, v34, v35
	v_lshrrev_b32_e32 v83, 16, v82
	s_waitcnt vmcnt(22)
	v_lshlrev_b32_e32 v84, 16, v84
	v_lshlrev_b32_e32 v116, 16, v116
	v_fmac_f32_e32 v36, v178, v84
	v_mul_f32_e32 v36, v36, v116
	s_waitcnt vmcnt(20)
	v_lshlrev_b32_e32 v85, 16, v85
	v_lshlrev_b32_e32 v117, 16, v117
	v_fmac_f32_e32 v37, v178, v85
	v_mul_f32_e32 v37, v37, v117
	v_cvt_pk_bf16_f32 v84, v36, v37
	v_lshrrev_b32_e32 v85, 16, v84
	s_waitcnt vmcnt(18)
	v_lshlrev_b32_e32 v86, 16, v86
	v_lshlrev_b32_e32 v118, 16, v118
	v_fmac_f32_e32 v38, v178, v86
	v_mul_f32_e32 v38, v38, v118
	s_waitcnt vmcnt(16)
	v_lshlrev_b32_e32 v87, 16, v87
	v_lshlrev_b32_e32 v119, 16, v119
	v_fmac_f32_e32 v39, v178, v87
	v_mul_f32_e32 v39, v39, v119
	v_cvt_pk_bf16_f32 v86, v38, v39
	v_lshrrev_b32_e32 v87, 16, v86
	s_waitcnt vmcnt(14)
	v_lshlrev_b32_e32 v88, 16, v88
	v_lshlrev_b32_e32 v120, 16, v120
	v_fmac_f32_e32 v40, v178, v88
	v_mul_f32_e32 v40, v40, v120
	s_waitcnt vmcnt(12)
	v_lshlrev_b32_e32 v89, 16, v89
	v_lshlrev_b32_e32 v121, 16, v121
	v_fmac_f32_e32 v41, v178, v89
	v_mul_f32_e32 v41, v41, v121
	v_cvt_pk_bf16_f32 v88, v40, v41
	v_lshrrev_b32_e32 v89, 16, v88
	s_waitcnt vmcnt(10)
	v_lshlrev_b32_e32 v90, 16, v90
	v_lshlrev_b32_e32 v122, 16, v122
	v_fmac_f32_e32 v42, v178, v90
	v_mul_f32_e32 v42, v42, v122
	s_waitcnt vmcnt(8)
	v_lshlrev_b32_e32 v91, 16, v91
	v_lshlrev_b32_e32 v123, 16, v123
	v_fmac_f32_e32 v43, v178, v91
	v_mul_f32_e32 v43, v43, v123
	v_cvt_pk_bf16_f32 v90, v42, v43
	v_lshrrev_b32_e32 v91, 16, v90
	s_waitcnt vmcnt(6)
	v_lshlrev_b32_e32 v92, 16, v92
	v_lshlrev_b32_e32 v124, 16, v124
	v_fmac_f32_e32 v44, v178, v92
	v_mul_f32_e32 v44, v44, v124
	s_waitcnt vmcnt(4)
	v_lshlrev_b32_e32 v93, 16, v93
	v_lshlrev_b32_e32 v125, 16, v125
	v_fmac_f32_e32 v45, v178, v93
	v_mul_f32_e32 v45, v45, v125
	v_cvt_pk_bf16_f32 v92, v44, v45
	v_lshrrev_b32_e32 v93, 16, v92
	s_waitcnt vmcnt(2)
	v_lshlrev_b32_e32 v94, 16, v94
	v_lshlrev_b32_e32 v126, 16, v126
	v_fmac_f32_e32 v46, v178, v94
	v_mul_f32_e32 v46, v46, v126
	s_waitcnt vmcnt(0)
; __device__ __forceinline__ unsigned pk2(float lo, float hi) { unsigned r; asm("v_cvt_pk_bf16_f32 %0, %1, %2" : "=v"(r) : "v"(lo), "v"(hi)); return r; }
; __device__ __forceinline__ float bf2f(bf16_t b) { return __uint_as_float(((unsigned)b) << 16); }
; template <int EPI>
; __device__ __forceinline__ void hy_conv(const Args& a, int L, int c, const bf16_t* U, LAS unsigned char* lds) {
;     ...
; #pragma unroll
;         for (int tt = 0; tt < 4; ++tt)
; #pragma unroll
;             for (int i = 0; i < 16; ++i) {
;                 const int bb = (i & 3) + 8 * (i >> 2) + 4 * h, t = 32 * (tb + tt) + n;
;                 const size_t tok = (size_t)bb * SEQ + t;
;                 if (EPI == 0) {
;                     const float v = bf2f(UC[(size_t)c * MTOK + tok]), x1 = bf2f(UC[((size_t)256 + c) * MTOK + tok]);
;                     const float z = x1 * (acc[tt][i] + dbias * v);
;                     Z[tok] = (bf16_t)(pk2(z, 0.f) & 0xffffu);
;                 } else {
;                     const float zz = bf2f(Z[tok]), x2 = bf2f(UC[((size_t)512 + c) * MTOK + tok]);
;                     const float o = x2 * (acc[tt][i] + dbias * zz);
;                     MIX[tok * DM + 384 + c] = (bf16_t)(pk2(o, 0.f) & 0xffffu);
;                 }
;             }
	v_lshlrev_b32_e32 v95, 16, v95
	v_lshlrev_b32_e32 v127, 16, v127
	v_fmac_f32_e32 v47, v178, v95
	v_mul_f32_e32 v47, v47, v127
	v_cvt_pk_bf16_f32 v94, v46, v47
	v_lshrrev_b32_e32 v95, 16, v94
	v_add_u32_e32 v141, 0x0, v143
	global_store_short v141, v64, s[20:21] offset:0
	v_add_u32_e32 v141, 0x1000, v143
	global_store_short v141, v65, s[20:21] offset:0
	v_add_u32_e32 v141, 0x2000, v143
	global_store_short v141, v66, s[20:21] offset:0
	v_add_u32_e32 v141, 0x3000, v143
	global_store_short v141, v67, s[20:21] offset:0
	v_add_u32_e32 v141, 0x8000, v143
	global_store_short v141, v68, s[20:21] offset:0
	v_add_u32_e32 v141, 0x9000, v143
	global_store_short v141, v69, s[20:21] offset:0
	v_add_u32_e32 v141, 0xa000, v143
	global_store_short v141, v70, s[20:21] offset:0
	v_add_u32_e32 v141, 0xb000, v143
	global_store_short v141, v71, s[20:21] offset:0
	v_add_u32_e32 v141, 0x10000, v143
	global_store_short v141, v72, s[20:21] offset:0
	v_add_u32_e32 v141, 0x11000, v143
	global_store_short v141, v73, s[20:21] offset:0
	v_add_u32_e32 v141, 0x12000, v143
	global_store_short v141, v74, s[20:21] offset:0
	v_add_u32_e32 v141, 0x13000, v143
	global_store_short v141, v75, s[20:21] offset:0
	v_add_u32_e32 v141, 0x18000, v143
	global_store_short v141, v76, s[20:21] offset:0
	v_add_u32_e32 v141, 0x19000, v143
	global_store_short v141, v77, s[20:21] offset:0
	v_add_u32_e32 v141, 0x1a000, v143
	global_store_short v141, v78, s[20:21] offset:0
	v_add_u32_e32 v141, 0x1b000, v143
	global_store_short v141, v79, s[20:21] offset:0
	v_add_u32_e32 v141, 0x0, v143
	global_store_short v141, v80, s[20:21] offset:64
	v_add_u32_e32 v141, 0x1000, v143
	global_store_short v141, v81, s[20:21] offset:64
	v_add_u32_e32 v141, 0x2000, v143
	global_store_short v141, v82, s[20:21] offset:64
	v_add_u32_e32 v141, 0x3000, v143
	global_store_short v141, v83, s[20:21] offset:64
	v_add_u32_e32 v141, 0x8000, v143
	global_store_short v141, v84, s[20:21] offset:64
	v_add_u32_e32 v141, 0x9000, v143
	global_store_short v141, v85, s[20:21] offset:64
	v_add_u32_e32 v141, 0xa000, v143
	global_store_short v141, v86, s[20:21] offset:64
	v_add_u32_e32 v141, 0xb000, v143
	global_store_short v141, v87, s[20:21] offset:64
	v_add_u32_e32 v141, 0x10000, v143
	global_store_short v141, v88, s[20:21] offset:64
	v_add_u32_e32 v141, 0x11000, v143
	global_store_short v141, v89, s[20:21] offset:64
	v_add_u32_e32 v141, 0x12000, v143
	global_store_short v141, v90, s[20:21] offset:64
	v_add_u32_e32 v141, 0x13000, v143
	global_store_short v141, v91, s[20:21] offset:64
	v_add_u32_e32 v141, 0x18000, v143
	global_store_short v141, v92, s[20:21] offset:64
	v_add_u32_e32 v141, 0x19000, v143
	global_store_short v141, v93, s[20:21] offset:64
	v_add_u32_e32 v141, 0x1a000, v143
	global_store_short v141, v94, s[20:21] offset:64
	v_add_u32_e32 v141, 0x1b000, v143
	global_store_short v141, v95, s[20:21] offset:64
	v_add_u32_e32 v141, 0x0, v143
	global_load_ushort v64, v141, s[0:1] offset:128
	global_load_ushort v96, v141, s[2:3] offset:128
	v_add_u32_e32 v141, 0x1000, v143
	global_load_ushort v65, v141, s[0:1] offset:128
	global_load_ushort v97, v141, s[2:3] offset:128
	v_add_u32_e32 v141, 0x2000, v143
	global_load_ushort v66, v141, s[0:1] offset:128
	global_load_ushort v98, v141, s[2:3] offset:128
	v_add_u32_e32 v141, 0x3000, v143
	global_load_ushort v67, v141, s[0:1] offset:128
	global_load_ushort v99, v141, s[2:3] offset:128
	v_add_u32_e32 v141, 0x8000, v143
	global_load_ushort v68, v141, s[0:1] offset:128
	global_load_ushort v100, v141, s[2:3] offset:128
	v_add_u32_e32 v141, 0x9000, v143
	global_load_ushort v69, v141, s[0:1] offset:128
	global_load_ushort v101, v141, s[2:3] offset:128
	v_add_u32_e32 v141, 0xa000, v143
	global_load_ushort v70, v141, s[0:1] offset:128
	global_load_ushort v102, v141, s[2:3] offset:128
	v_add_u32_e32 v141, 0xb000, v143
	global_load_ushort v71, v141, s[0:1] offset:128
	global_load_ushort v103, v141, s[2:3] offset:128
	v_add_u32_e32 v141, 0x10000, v143
	global_load_ushort v72, v141, s[0:1] offset:128
	global_load_ushort v104, v141, s[2:3] offset:128
	v_add_u32_e32 v141, 0x11000, v143
	global_load_ushort v73, v141, s[0:1] offset:128
	global_load_ushort v105, v141, s[2:3] offset:128
	v_add_u32_e32 v141, 0x12000, v143
	global_load_ushort v74, v141, s[0:1] offset:128
	global_load_ushort v106, v141, s[2:3] offset:128
	v_add_u32_e32 v141, 0x13000, v143
	global_load_ushort v75, v141, s[0:1] offset:128
	global_load_ushort v107, v141, s[2:3] offset:128
	v_add_u32_e32 v141, 0x18000, v143
	global_load_ushort v76, v141, s[0:1] offset:128
	global_load_ushort v108, v141, s[2:3] offset:128
	v_add_u32_e32 v141, 0x19000, v143
	global_load_ushort v77, v141, s[0:1] offset:128
	global_load_ushort v109, v141, s[2:3] offset:128
	v_add_u32_e32 v141, 0x1a000, v143
	global_load_ushort v78, v141, s[0:1] offset:128
	global_load_ushort v110, v141, s[2:3] offset:128
	v_add_u32_e32 v141, 0x1b000, v143
	global_load_ushort v79, v141, s[0:1] offset:128
	global_load_ushort v111, v141, s[2:3] offset:128
	v_add_u32_e32 v141, 0x0, v143
	global_load_ushort v80, v141, s[0:1] offset:192
	global_load_ushort v112, v141, s[2:3] offset:192
	v_add_u32_e32 v141, 0x1000, v143
	global_load_ushort v81, v141, s[0:1] offset:192
	global_load_ushort v113, v141, s[2:3] offset:192
	v_add_u32_e32 v141, 0x2000, v143
	global_load_ushort v82, v141, s[0:1] offset:192
	global_load_ushort v114, v141, s[2:3] offset:192
	v_add_u32_e32 v141, 0x3000, v143
	global_load_ushort v83, v141, s[0:1] offset:192
	global_load_ushort v115, v141, s[2:3] offset:192
	v_add_u32_e32 v141, 0x8000, v143
	global_load_ushort v84, v141, s[0:1] offset:192
; __device__ __forceinline__ unsigned pk2(float lo, float hi) { unsigned r; asm("v_cvt_pk_bf16_f32 %0, %1, %2" : "=v"(r) : "v"(lo), "v"(hi)); return r; }
; __device__ __forceinline__ float bf2f(bf16_t b) { return __uint_as_float(((unsigned)b) << 16); }
; template <int EPI>
; __device__ __forceinline__ void hy_conv(const Args& a, int L, int c, const bf16_t* U, LAS unsigned char* lds) {
;     ...
; #pragma unroll
;         for (int tt = 0; tt < 4; ++tt)
; #pragma unroll
;             for (int i = 0; i < 16; ++i) {
;                 const int bb = (i & 3) + 8 * (i >> 2) + 4 * h, t = 32 * (tb + tt) + n;
;                 const size_t tok = (size_t)bb * SEQ + t;
;                 if (EPI == 0) {
;                     const float v = bf2f(UC[(size_t)c * MTOK + tok]), x1 = bf2f(UC[((size_t)256 + c) * MTOK + tok]);
;                     const float z = x1 * (acc[tt][i] + dbias * v);
;                     Z[tok] = (bf16_t)(pk2(z, 0.f) & 0xffffu);
;                 } else {
;                     const float zz = bf2f(Z[tok]), x2 = bf2f(UC[((size_t)512 + c) * MTOK + tok]);
;                     const float o = x2 * (acc[tt][i] + dbias * zz);
;                     MIX[tok * DM + 384 + c] = (bf16_t)(pk2(o, 0.f) & 0xffffu);
;                 }
;             }
	global_load_ushort v116, v141, s[2:3] offset:192
	v_add_u32_e32 v141, 0x9000, v143
	global_load_ushort v85, v141, s[0:1] offset:192
	global_load_ushort v117, v141, s[2:3] offset:192
	v_add_u32_e32 v141, 0xa000, v143
	global_load_ushort v86, v141, s[0:1] offset:192
	global_load_ushort v118, v141, s[2:3] offset:192
	v_add_u32_e32 v141, 0xb000, v143
	global_load_ushort v87, v141, s[0:1] offset:192
	global_load_ushort v119, v141, s[2:3] offset:192
	v_add_u32_e32 v141, 0x10000, v143
	global_load_ushort v88, v141, s[0:1] offset:192
	global_load_ushort v120, v141, s[2:3] offset:192
	v_add_u32_e32 v141, 0x11000, v143
	global_load_ushort v89, v141, s[0:1] offset:192
	global_load_ushort v121, v141, s[2:3] offset:192
	v_add_u32_e32 v141, 0x12000, v143
	global_load_ushort v90, v141, s[0:1] offset:192
	global_load_ushort v122, v141, s[2:3] offset:192
	v_add_u32_e32 v141, 0x13000, v143
	global_load_ushort v91, v141, s[0:1] offset:192
	global_load_ushort v123, v141, s[2:3] offset:192
	v_add_u32_e32 v141, 0x18000, v143
	global_load_ushort v92, v141, s[0:1] offset:192
	global_load_ushort v124, v141, s[2:3] offset:192
	v_add_u32_e32 v141, 0x19000, v143
	global_load_ushort v93, v141, s[0:1] offset:192
	global_load_ushort v125, v141, s[2:3] offset:192
	v_add_u32_e32 v141, 0x1a000, v143
	global_load_ushort v94, v141, s[0:1] offset:192
	global_load_ushort v126, v141, s[2:3] offset:192
	v_add_u32_e32 v141, 0x1b000, v143
	global_load_ushort v95, v141, s[0:1] offset:192
	global_load_ushort v127, v141, s[2:3] offset:192
	s_waitcnt vmcnt(62)
	v_lshlrev_b32_e32 v64, 16, v64
	v_lshlrev_b32_e32 v96, 16, v96
	v_fmac_f32_e32 v16, v178, v64
	v_mul_f32_e32 v16, v16, v96
	s_waitcnt vmcnt(60)
	v_lshlrev_b32_e32 v65, 16, v65
	v_lshlrev_b32_e32 v97, 16, v97
	v_fmac_f32_e32 v17, v178, v65
	v_mul_f32_e32 v17, v17, v97
	v_cvt_pk_bf16_f32 v64, v16, v17
	v_lshrrev_b32_e32 v65, 16, v64
	s_waitcnt vmcnt(58)
	v_lshlrev_b32_e32 v66, 16, v66
	v_lshlrev_b32_e32 v98, 16, v98
	v_fmac_f32_e32 v18, v178, v66
	v_mul_f32_e32 v18, v18, v98
	s_waitcnt vmcnt(56)
	v_lshlrev_b32_e32 v67, 16, v67
	v_lshlrev_b32_e32 v99, 16, v99
	v_fmac_f32_e32 v19, v178, v67
	v_mul_f32_e32 v19, v19, v99
	v_cvt_pk_bf16_f32 v66, v18, v19
	v_lshrrev_b32_e32 v67, 16, v66
	s_waitcnt vmcnt(54)
	v_lshlrev_b32_e32 v68, 16, v68
	v_lshlrev_b32_e32 v100, 16, v100
	v_fmac_f32_e32 v20, v178, v68
	v_mul_f32_e32 v20, v20, v100
	s_waitcnt vmcnt(52)
	v_lshlrev_b32_e32 v69, 16, v69
	v_lshlrev_b32_e32 v101, 16, v101
	v_fmac_f32_e32 v21, v178, v69
	v_mul_f32_e32 v21, v21, v101
	v_cvt_pk_bf16_f32 v68, v20, v21
	v_lshrrev_b32_e32 v69, 16, v68
	s_waitcnt vmcnt(50)
	v_lshlrev_b32_e32 v70, 16, v70
	v_lshlrev_b32_e32 v102, 16, v102
	v_fmac_f32_e32 v22, v178, v70
	v_mul_f32_e32 v22, v22, v102
	s_waitcnt vmcnt(48)
	v_lshlrev_b32_e32 v71, 16, v71
	v_lshlrev_b32_e32 v103, 16, v103
	v_fmac_f32_e32 v23, v178, v71
	v_mul_f32_e32 v23, v23, v103
	v_cvt_pk_bf16_f32 v70, v22, v23
	v_lshrrev_b32_e32 v71, 16, v70
	s_waitcnt vmcnt(46)
	v_lshlrev_b32_e32 v72, 16, v72
	v_lshlrev_b32_e32 v104, 16, v104
	v_fmac_f32_e32 v24, v178, v72
	v_mul_f32_e32 v24, v24, v104
	s_waitcnt vmcnt(44)
	v_lshlrev_b32_e32 v73, 16, v73
	v_lshlrev_b32_e32 v105, 16, v105
	v_fmac_f32_e32 v25, v178, v73
	v_mul_f32_e32 v25, v25, v105
	v_cvt_pk_bf16_f32 v72, v24, v25
	v_lshrrev_b32_e32 v73, 16, v72
	s_waitcnt vmcnt(42)
	v_lshlrev_b32_e32 v74, 16, v74
	v_lshlrev_b32_e32 v106, 16, v106
	v_fmac_f32_e32 v26, v178, v74
	v_mul_f32_e32 v26, v26, v106
	s_waitcnt vmcnt(40)
	v_lshlrev_b32_e32 v75, 16, v75
	v_lshlrev_b32_e32 v107, 16, v107
	v_fmac_f32_e32 v27, v178, v75
	v_mul_f32_e32 v27, v27, v107
	v_cvt_pk_bf16_f32 v74, v26, v27
	v_lshrrev_b32_e32 v75, 16, v74
	s_waitcnt vmcnt(38)
	v_lshlrev_b32_e32 v76, 16, v76
	v_lshlrev_b32_e32 v108, 16, v108
	v_fmac_f32_e32 v28, v178, v76
	v_mul_f32_e32 v28, v28, v108
	s_waitcnt vmcnt(36)
	v_lshlrev_b32_e32 v77, 16, v77
	v_lshlrev_b32_e32 v109, 16, v109
	v_fmac_f32_e32 v29, v178, v77
	v_mul_f32_e32 v29, v29, v109
	v_cvt_pk_bf16_f32 v76, v28, v29
	v_lshrrev_b32_e32 v77, 16, v76
	s_waitcnt vmcnt(34)
	v_lshlrev_b32_e32 v78, 16, v78
	v_lshlrev_b32_e32 v110, 16, v110
	v_fmac_f32_e32 v30, v178, v78
	v_mul_f32_e32 v30, v30, v110
	s_waitcnt vmcnt(32)
	v_lshlrev_b32_e32 v79, 16, v79
	v_lshlrev_b32_e32 v111, 16, v111
	v_fmac_f32_e32 v31, v178, v79
	v_mul_f32_e32 v31, v31, v111
	v_cvt_pk_bf16_f32 v78, v30, v31
	v_lshrrev_b32_e32 v79, 16, v78
	s_waitcnt vmcnt(30)
	v_lshlrev_b32_e32 v80, 16, v80
	v_lshlrev_b32_e32 v112, 16, v112
	v_fmac_f32_e32 v0, v178, v80
	v_mul_f32_e32 v0, v0, v112
	s_waitcnt vmcnt(28)
	v_lshlrev_b32_e32 v81, 16, v81
	v_lshlrev_b32_e32 v113, 16, v113
	v_fmac_f32_e32 v1, v178, v81
	v_mul_f32_e32 v1, v1, v113
	v_cvt_pk_bf16_f32 v80, v0, v1
	v_lshrrev_b32_e32 v81, 16, v80
	s_waitcnt vmcnt(26)
	v_lshlrev_b32_e32 v82, 16, v82
	v_lshlrev_b32_e32 v114, 16, v114
	v_fmac_f32_e32 v2, v178, v82
	v_mul_f32_e32 v2, v2, v114
	s_waitcnt vmcnt(24)
	v_lshlrev_b32_e32 v83, 16, v83
	v_lshlrev_b32_e32 v115, 16, v115
	v_fmac_f32_e32 v3, v178, v83
	v_mul_f32_e32 v3, v3, v115
	v_cvt_pk_bf16_f32 v82, v2, v3
	v_lshrrev_b32_e32 v83, 16, v82
	s_waitcnt vmcnt(22)
	v_lshlrev_b32_e32 v84, 16, v84
	v_lshlrev_b32_e32 v116, 16, v116
	v_fmac_f32_e32 v4, v178, v84
	v_mul_f32_e32 v4, v4, v116
	s_waitcnt vmcnt(20)
	v_lshlrev_b32_e32 v85, 16, v85
	v_lshlrev_b32_e32 v117, 16, v117
	v_fmac_f32_e32 v5, v178, v85
	v_mul_f32_e32 v5, v5, v117
	v_cvt_pk_bf16_f32 v84, v4, v5
	v_lshrrev_b32_e32 v85, 16, v84
	s_waitcnt vmcnt(18)
	v_lshlrev_b32_e32 v86, 16, v86
	v_lshlrev_b32_e32 v118, 16, v118
	v_fmac_f32_e32 v6, v178, v86
	v_mul_f32_e32 v6, v6, v118
	s_waitcnt vmcnt(16)
; __device__ __forceinline__ unsigned pk2(float lo, float hi) { unsigned r; asm("v_cvt_pk_bf16_f32 %0, %1, %2" : "=v"(r) : "v"(lo), "v"(hi)); return r; }
; __device__ __forceinline__ float bf2f(bf16_t b) { return __uint_as_float(((unsigned)b) << 16); }
; template <int EPI>
; __device__ __forceinline__ void hy_conv(const Args& a, int L, int c, const bf16_t* U, LAS unsigned char* lds) {
;     ...
; #pragma unroll
;         for (int tt = 0; tt < 4; ++tt)
; #pragma unroll
;             for (int i = 0; i < 16; ++i) {
;                 const int bb = (i & 3) + 8 * (i >> 2) + 4 * h, t = 32 * (tb + tt) + n;
;                 const size_t tok = (size_t)bb * SEQ + t;
;                 if (EPI == 0) {
;                     const float v = bf2f(UC[(size_t)c * MTOK + tok]), x1 = bf2f(UC[((size_t)256 + c) * MTOK + tok]);
;                     const float z = x1 * (acc[tt][i] + dbias * v);
;                     Z[tok] = (bf16_t)(pk2(z, 0.f) & 0xffffu);
;                 } else {
;                     const float zz = bf2f(Z[tok]), x2 = bf2f(UC[((size_t)512 + c) * MTOK + tok]);
;                     const float o = x2 * (acc[tt][i] + dbias * zz);
;                     MIX[tok * DM + 384 + c] = (bf16_t)(pk2(o, 0.f) & 0xffffu);
;                 }
;             }
;     }
; }
	v_lshlrev_b32_e32 v87, 16, v87
	v_lshlrev_b32_e32 v119, 16, v119
	v_fmac_f32_e32 v7, v178, v87
	v_mul_f32_e32 v7, v7, v119
	v_cvt_pk_bf16_f32 v86, v6, v7
	v_lshrrev_b32_e32 v87, 16, v86
	s_waitcnt vmcnt(14)
	v_lshlrev_b32_e32 v88, 16, v88
	v_lshlrev_b32_e32 v120, 16, v120
	v_fmac_f32_e32 v8, v178, v88
	v_mul_f32_e32 v8, v8, v120
	s_waitcnt vmcnt(12)
	v_lshlrev_b32_e32 v89, 16, v89
	v_lshlrev_b32_e32 v121, 16, v121
	v_fmac_f32_e32 v9, v178, v89
	v_mul_f32_e32 v9, v9, v121
	v_cvt_pk_bf16_f32 v88, v8, v9
	v_lshrrev_b32_e32 v89, 16, v88
	s_waitcnt vmcnt(10)
	v_lshlrev_b32_e32 v90, 16, v90
	v_lshlrev_b32_e32 v122, 16, v122
	v_fmac_f32_e32 v10, v178, v90
	v_mul_f32_e32 v10, v10, v122
	s_waitcnt vmcnt(8)
	v_lshlrev_b32_e32 v91, 16, v91
	v_lshlrev_b32_e32 v123, 16, v123
	v_fmac_f32_e32 v11, v178, v91
	v_mul_f32_e32 v11, v11, v123
	v_cvt_pk_bf16_f32 v90, v10, v11
	v_lshrrev_b32_e32 v91, 16, v90
	s_waitcnt vmcnt(6)
	v_lshlrev_b32_e32 v92, 16, v92
	v_lshlrev_b32_e32 v124, 16, v124
	v_fmac_f32_e32 v12, v178, v92
	v_mul_f32_e32 v12, v12, v124
	s_waitcnt vmcnt(4)
	v_lshlrev_b32_e32 v93, 16, v93
	v_lshlrev_b32_e32 v125, 16, v125
	v_fmac_f32_e32 v13, v178, v93
	v_mul_f32_e32 v13, v13, v125
	v_cvt_pk_bf16_f32 v92, v12, v13
	v_lshrrev_b32_e32 v93, 16, v92
	s_waitcnt vmcnt(2)
	v_lshlrev_b32_e32 v94, 16, v94
	v_lshlrev_b32_e32 v126, 16, v126
	v_fmac_f32_e32 v14, v178, v94
	v_mul_f32_e32 v14, v14, v126
	s_waitcnt vmcnt(0)
	v_lshlrev_b32_e32 v95, 16, v95
	v_lshlrev_b32_e32 v127, 16, v127
	v_fmac_f32_e32 v15, v178, v95
	v_mul_f32_e32 v15, v15, v127
	v_cvt_pk_bf16_f32 v94, v14, v15
	v_lshrrev_b32_e32 v95, 16, v94
	v_add_u32_e32 v141, 0x0, v143
	global_store_short v141, v64, s[20:21] offset:128
	v_add_u32_e32 v141, 0x1000, v143
	global_store_short v141, v65, s[20:21] offset:128
	v_add_u32_e32 v141, 0x2000, v143
	global_store_short v141, v66, s[20:21] offset:128
	v_add_u32_e32 v141, 0x3000, v143
	global_store_short v141, v67, s[20:21] offset:128
	v_add_u32_e32 v141, 0x8000, v143
	global_store_short v141, v68, s[20:21] offset:128
	v_add_u32_e32 v141, 0x9000, v143
	global_store_short v141, v69, s[20:21] offset:128
	v_add_u32_e32 v141, 0xa000, v143
	global_store_short v141, v70, s[20:21] offset:128
	v_add_u32_e32 v141, 0xb000, v143
	global_store_short v141, v71, s[20:21] offset:128
	v_add_u32_e32 v141, 0x10000, v143
	global_store_short v141, v72, s[20:21] offset:128
	v_add_u32_e32 v141, 0x11000, v143
	global_store_short v141, v73, s[20:21] offset:128
	v_add_u32_e32 v141, 0x12000, v143
	global_store_short v141, v74, s[20:21] offset:128
	v_add_u32_e32 v141, 0x13000, v143
	global_store_short v141, v75, s[20:21] offset:128
	v_add_u32_e32 v141, 0x18000, v143
	global_store_short v141, v76, s[20:21] offset:128
	v_add_u32_e32 v141, 0x19000, v143
	global_store_short v141, v77, s[20:21] offset:128
	v_add_u32_e32 v141, 0x1a000, v143
	global_store_short v141, v78, s[20:21] offset:128
	v_add_u32_e32 v141, 0x1b000, v143
	global_store_short v141, v79, s[20:21] offset:128
	v_add_u32_e32 v141, 0x0, v143
	global_store_short v141, v80, s[20:21] offset:192
	v_add_u32_e32 v141, 0x1000, v143
	global_store_short v141, v81, s[20:21] offset:192
	v_add_u32_e32 v141, 0x2000, v143
	global_store_short v141, v82, s[20:21] offset:192
	v_add_u32_e32 v141, 0x3000, v143
	global_store_short v141, v83, s[20:21] offset:192
	v_add_u32_e32 v141, 0x8000, v143
	global_store_short v141, v84, s[20:21] offset:192
	v_add_u32_e32 v141, 0x9000, v143
	global_store_short v141, v85, s[20:21] offset:192
	v_add_u32_e32 v141, 0xa000, v143
	global_store_short v141, v86, s[20:21] offset:192
	v_add_u32_e32 v141, 0xb000, v143
	global_store_short v141, v87, s[20:21] offset:192
	v_add_u32_e32 v141, 0x10000, v143
	global_store_short v141, v88, s[20:21] offset:192
	v_add_u32_e32 v141, 0x11000, v143
	global_store_short v141, v89, s[20:21] offset:192
	v_add_u32_e32 v141, 0x12000, v143
	global_store_short v141, v90, s[20:21] offset:192
	v_add_u32_e32 v141, 0x13000, v143
	global_store_short v141, v91, s[20:21] offset:192
	v_add_u32_e32 v141, 0x18000, v143
	global_store_short v141, v92, s[20:21] offset:192
	v_add_u32_e32 v141, 0x19000, v143
	global_store_short v141, v93, s[20:21] offset:192
	v_add_u32_e32 v141, 0x1a000, v143
	global_store_short v141, v94, s[20:21] offset:192
	v_add_u32_e32 v141, 0x1b000, v143
	global_store_short v141, v95, s[20:21] offset:192
	s_cmp_eq_u32 s26, 16
	s_cbranch_scc1 .Lhc1_done
	v_mov_b32_e32 v0, 0
	v_mov_b32_e32 v1, 0
	v_mov_b32_e32 v2, 0
	v_mov_b32_e32 v3, 0
	v_mov_b32_e32 v4, 0
	v_mov_b32_e32 v5, 0
	v_mov_b32_e32 v6, 0
	v_mov_b32_e32 v7, 0
	v_mov_b32_e32 v8, 0
	v_mov_b32_e32 v9, 0
	v_mov_b32_e32 v10, 0
	v_mov_b32_e32 v11, 0
	v_mov_b32_e32 v12, 0
	v_mov_b32_e32 v13, 0
	v_mov_b32_e32 v14, 0
	v_mov_b32_e32 v15, 0
	v_mov_b32_e32 v16, 0
	v_mov_b32_e32 v17, 0
	v_mov_b32_e32 v18, 0
	v_mov_b32_e32 v19, 0
	v_mov_b32_e32 v20, 0
	v_mov_b32_e32 v21, 0
	v_mov_b32_e32 v22, 0
	v_mov_b32_e32 v23, 0
	v_mov_b32_e32 v24, 0
	v_mov_b32_e32 v25, 0
	v_mov_b32_e32 v26, 0
	v_mov_b32_e32 v27, 0
	v_mov_b32_e32 v28, 0
	v_mov_b32_e32 v29, 0
	v_mov_b32_e32 v30, 0
	v_mov_b32_e32 v31, 0
	v_mov_b32_e32 v32, 0
	v_mov_b32_e32 v33, 0
	v_mov_b32_e32 v34, 0
	v_mov_b32_e32 v35, 0
	v_mov_b32_e32 v36, 0
	v_mov_b32_e32 v37, 0
	v_mov_b32_e32 v38, 0
	v_mov_b32_e32 v39, 0
	v_mov_b32_e32 v40, 0
	v_mov_b32_e32 v41, 0
	v_mov_b32_e32 v42, 0
	v_mov_b32_e32 v43, 0
	v_mov_b32_e32 v44, 0
	v_mov_b32_e32 v45, 0
	v_mov_b32_e32 v46, 0
	v_mov_b32_e32 v47, 0
	v_mov_b32_e32 v48, 0
	v_mov_b32_e32 v49, 0
	v_mov_b32_e32 v50, 0
	v_mov_b32_e32 v51, 0
	v_mov_b32_e32 v52, 0
	v_mov_b32_e32 v53, 0
	v_mov_b32_e32 v54, 0
	v_mov_b32_e32 v55, 0
	v_mov_b32_e32 v56, 0
	v_mov_b32_e32 v57, 0
	v_mov_b32_e32 v58, 0
	v_mov_b32_e32 v59, 0
	v_mov_b32_e32 v60, 0
	v_mov_b32_e32 v61, 0
	v_mov_b32_e32 v62, 0
	v_mov_b32_e32 v63, 0
	v_add_u32_e32 v214, 0xffffff00, v212
	s_branch .Lhc1_blk

; __device__ __forceinline__ unsigned xb_xcc_id() { return (unsigned)__builtin_amdgcn_s_getreg((3 << 11) | 20) & 0xFu; }
; __global__ __launch_bounds__(512, 2) void mk_fwd(Args a) {
;     ...
;     for (int ph = a.ph_lo; ph < a.ph_hi; ++ph) {
;         run_phase(a, ph, lds);
;         if (a.coop && ph + 1 < a.ph_hi) {
;             if (ph == 0) cg::this_grid().sync();
;             else xcd_barrier(bar, xb_xcc_id(), ph == 1);
;         }
;     }
.LBB0_422:
	v_readlane_b32 s2, v255, 63
	s_cmp_eq_u32 s76, 2
	s_cselect_b32 s3, 1, 0
	s_cmp_eq_u32 s76, 9
	s_cselect_b32 s22, 1, 0
	s_or_b32 s3, s3, s22
	s_andn2_b32 s3, s3, s2
	s_nop 0
	v_writelane_b32 v255, s3, 63
	s_sub_i32 s22, s76, s3
	s_add_i32 s22, s22, 1
	s_cmp_ge_i32 s22, s77
	s_cselect_b64 s[0:1], -1, 0
	s_cmp_lt_i32 s22, s77
	v_readlane_b32 s4, v253, 0
	s_cselect_b64 s[2:3], -1, 0
	v_readlane_b32 s5, v253, 1
	s_and_b64 s[2:3], s[4:5], s[2:3]
	s_andn2_b64 vcc, exec, s[2:3]
	s_cbranch_vccz .LBB0_423
	s_getpc_b64 s[98:99]
